# sample-attention items: all row loads in flight + DPP reductions; memattn K/V staging loads batched
# speedup vs baseline: 1.0195x; 1.0195x over previous
.LBB0_109:
	s_cmpk_gt_u32 s51, 0x3e8
	s_cselect_b64 s[2:3], -1, 0
	s_add_u32 s0, s0, 0x130
	s_addc_u32 s1, s1, 0
	v_writelane_b32 v254, s0, 1
	v_lshrrev_b32_e32 v2, 20, v0
	v_lshrrev_b32_e32 v0, 10, v0
	v_writelane_b32 v254, s1, 2
	s_lshl_b32 s0, s26, 6
	v_writelane_b32 v254, s0, 3
	s_add_i32 s0, 0, 0x23f20
	v_writelane_b32 v254, s0, 4
	s_add_i32 s0, 0, 0x23f40
	v_writelane_b32 v254, s0, 5
	s_add_i32 s0, 0, 0x23f44
	v_writelane_b32 v254, s0, 6
	s_add_i32 s0, 0, 0x23f00
	v_writelane_b32 v254, s0, 7
	s_add_i32 s0, 0, 0x23f18
	v_writelane_b32 v254, s0, 8
	s_add_i32 s0, 0, 0x23e20
	v_writelane_b32 v254, s0, 9
	s_add_i32 s0, 0, 0x23e08
	v_writelane_b32 v254, s0, 10
	s_add_i32 s0, 0, 0x23e38
	v_writelane_b32 v254, s0, 11
	s_add_i32 s1, 0, 0x44c0
	v_writelane_b32 v254, s1, 12
	s_add_i32 s1, 0, 0x23e28
	v_writelane_b32 v254, s1, 13
	s_add_i32 s1, 0, 0x23ea8
	v_writelane_b32 v254, s1, 14
	s_add_i32 s1, 0, 0x23ec8
	v_writelane_b32 v254, s1, 15
	s_add_i32 s1, 0, 0x1010
	v_writelane_b32 v254, s1, 16
	s_add_i32 s1, 0, 0x23eb0
	v_writelane_b32 v254, s1, 17
	s_add_i32 s1, 0, 0x23ee8
	v_writelane_b32 v254, s1, 18
	s_add_i32 s1, 0, 0x23e68
	v_writelane_b32 v254, s1, 19
	s_add_i32 s1, 0, 0x1cc00
	v_writelane_b32 v254, s1, 20
	s_add_i32 s1, 0, 0x23e90
	v_writelane_b32 v254, s1, 21
	s_add_i32 s1, 0, 0x23e80
	v_writelane_b32 v254, s1, 22
	s_add_i32 s1, 0, 0x23e18
	v_writelane_b32 v254, s1, 23
	s_add_i32 s1, 0, 0x18400
	v_writelane_b32 v254, s1, 24
	s_add_i32 s1, 0, 0x8400
	v_writelane_b32 v254, s1, 25
	s_add_i32 s1, 0, 0x10400
	v_or_b32_e32 v0, v0, v2
	s_movk_i32 s4, 0x3ff
	v_writelane_b32 v254, s1, 26
	s_add_i32 s1, 0, 0x23e10
	v_and_or_b32 v0, v0, s4, v1
	v_writelane_b32 v254, s1, 27
	s_add_i32 s1, 0, 0x21400
	v_cndmask_b32_e64 v2, 0, 1, s[2:3]
	v_writelane_b32 v254, s1, 28
	v_cmp_eq_u32_e64 s[2:3], 0, v0
	s_add_i32 s0, 0, 0x23ee0
	v_mbcnt_lo_u32_b32 v3, -1, 0
	v_writelane_b32 v254, s2, 29
	v_mbcnt_hi_u32_b32 v223, -1, v3
	v_mov_b32_e32 v1, 0
	v_writelane_b32 v254, s3, 30
	v_cmp_ne_u32_e64 s[2:3], 1, v2
	s_mov_b32 s33, 0xffff0000
	v_mov_b32_e32 v218, 1
	v_writelane_b32 v254, s2, 31
	v_mov_b32_e32 v219, 0x358637bd
	v_mov_b32_e32 v220, 0xc0135761
	v_writelane_b32 v254, s3, 32
	v_writelane_b32 v254, s50, 33
	s_movk_i32 s87, 0xbf
	s_mov_b32 s85, 0xf800000
	v_writelane_b32 v254, s51, 34
	v_mov_b32_e32 v221, 0x260
	s_movk_i32 s91, 0x7fff
	s_movk_i32 s88, 0x90
	s_mov_b32 s89, 0xf149f2ca
	v_mov_b32_e32 v222, 0x3ecc95a3
	v_sub_u32_e32 v224, 0, v223
	v_mov_b32_e32 v225, 0xc000
	v_mov_b32_e32 v226, 0x12000
	v_mov_b64_e32 v[198:199], 0xff
	v_mov_b32_e32 v227, 0xf149f2ca
	v_mov_b32_e32 v4, 1.0
	v_mov_b32_e32 v228, 0x7f800000
	s_mov_b32 s95, 0
	s_mov_b64 s[96:97], 0x80
	s_mov_b32 s86, 0x3e000000
	v_writelane_b32 v254, s0, 35
	s_branch .LBB0_112
.Lexit_near:
	s_endpgm
.LBB0_110:
	v_readlane_b32 s56, v254, 44

.LBB0_407:
	s_or_b64 exec, exec, s[0:1]
	s_movk_i32 s0, 0x100
	v_lshrrev_b32_e32 v12, 4, v22
	v_and_b32_e32 v10, 15, v78
	v_cmp_gt_i32_e32 vcc, s0, v6
	s_waitcnt lgkmcnt(0)
	s_barrier
	s_and_saveexec_b64 s[0:1], vcc
	s_cbranch_execz .LBB0_412
	v_mul_u32_u24_e32 v7, 0x410, v12
	v_lshlrev_b32_e32 v8, 2, v6
	s_add_i32 s2, 0, 0xc00
	v_add3_u32 v11, v7, v8, s2
	v_readlane_b32 s2, v254, 56
	v_readlane_b32 s3, v254, 57
	s_add_u32 s2, s12, s2
	v_readlane_b32 s6, v254, 55
	s_addc_u32 s3, s13, s3
	s_add_i32 s94, s21, s6
	v_ashrrev_i32_e32 v7, 31, v6
	s_lshl_b64 s[6:7], s[94:95], 18
	v_lshlrev_b64 v[8:9], 10, v[6:7]
	v_lshl_add_u64 v[8:9], s[6:7], 0, v[8:9]
	v_lshl_add_u32 v13, v10, 4, 0
	v_lshlrev_b32_e32 v14, 8, v12
	v_lshl_or_b32 v8, v22, 4, v8
	v_cmp_eq_u32_e32 vcc, 0, v10
	v_lshl_add_u64 v[8:9], s[2:3], 0, v[8:9]
	s_mov_b64 s[2:3], 0
	v_add_u32_e32 v7, v13, v14
	s_mov_b64 s[6:7], 0x2000
	ds_read_b128 v[18:21], v7
	global_load_dwordx4 v[132:135], v[8:9], off nt
	v_lshl_add_u64 v[8:9], v[8:9], 0, s[6:7]
	global_load_dwordx4 v[136:139], v[8:9], off nt
	v_lshl_add_u64 v[8:9], v[8:9], 0, s[6:7]
	global_load_dwordx4 v[140:143], v[8:9], off nt
	v_lshl_add_u64 v[8:9], v[8:9], 0, s[6:7]
	global_load_dwordx4 v[144:147], v[8:9], off nt
	v_lshl_add_u64 v[8:9], v[8:9], 0, s[6:7]
	global_load_dwordx4 v[148:151], v[8:9], off nt
	v_lshl_add_u64 v[8:9], v[8:9], 0, s[6:7]
	global_load_dwordx4 v[152:155], v[8:9], off nt
	v_lshl_add_u64 v[8:9], v[8:9], 0, s[6:7]
	global_load_dwordx4 v[156:159], v[8:9], off nt
	v_lshl_add_u64 v[8:9], v[8:9], 0, s[6:7]
	global_load_dwordx4 v[160:163], v[8:9], off nt
	v_lshl_add_u64 v[8:9], v[8:9], 0, s[6:7]
	global_load_dwordx4 v[164:167], v[8:9], off nt
	v_lshl_add_u64 v[8:9], v[8:9], 0, s[6:7]
	global_load_dwordx4 v[168:171], v[8:9], off nt
	v_lshl_add_u64 v[8:9], v[8:9], 0, s[6:7]
	global_load_dwordx4 v[172:175], v[8:9], off nt
	v_lshl_add_u64 v[8:9], v[8:9], 0, s[6:7]
	global_load_dwordx4 v[176:179], v[8:9], off nt
	v_lshl_add_u64 v[8:9], v[8:9], 0, s[6:7]
	global_load_dwordx4 v[180:183], v[8:9], off nt
	v_lshl_add_u64 v[8:9], v[8:9], 0, s[6:7]
	global_load_dwordx4 v[184:187], v[8:9], off nt
	v_lshl_add_u64 v[8:9], v[8:9], 0, s[6:7]
	global_load_dwordx4 v[188:191], v[8:9], off nt
	v_lshl_add_u64 v[8:9], v[8:9], 0, s[6:7]
	global_load_dwordx4 v[192:195], v[8:9], off nt
	v_lshl_add_u64 v[8:9], v[8:9], 0, s[6:7]
	s_waitcnt vmcnt(15) lgkmcnt(0)
	v_mul_f32_e32 v200, v133, v19
	v_mul_f32_e32 v216, v135, v21
	v_fmac_f32_e32 v200, v132, v18
	v_fmac_f32_e32 v216, v134, v20
	v_add_f32_e32 v200, v200, v216
	global_load_dwordx4 v[132:135], v[8:9], off nt
	v_lshl_add_u64 v[8:9], v[8:9], 0, s[6:7]
	s_waitcnt vmcnt(15)
	v_mul_f32_e32 v201, v137, v19
	v_mul_f32_e32 v216, v139, v21
	v_fmac_f32_e32 v201, v136, v18
	v_fmac_f32_e32 v216, v138, v20
	v_add_f32_e32 v201, v201, v216
	global_load_dwordx4 v[136:139], v[8:9], off nt
	v_lshl_add_u64 v[8:9], v[8:9], 0, s[6:7]
	s_waitcnt vmcnt(15)
	v_mul_f32_e32 v202, v141, v19
	v_mul_f32_e32 v216, v143, v21
	v_fmac_f32_e32 v202, v140, v18
	v_fmac_f32_e32 v216, v142, v20
	v_add_f32_e32 v202, v202, v216
	global_load_dwordx4 v[140:143], v[8:9], off nt
	v_lshl_add_u64 v[8:9], v[8:9], 0, s[6:7]
	s_waitcnt vmcnt(15)
	v_mul_f32_e32 v203, v145, v19
	v_mul_f32_e32 v216, v147, v21
	v_fmac_f32_e32 v203, v144, v18
	v_fmac_f32_e32 v216, v146, v20
	v_add_f32_e32 v203, v203, v216
	global_load_dwordx4 v[144:147], v[8:9], off nt
	v_lshl_add_u64 v[8:9], v[8:9], 0, s[6:7]
	s_waitcnt vmcnt(15)
	v_mul_f32_e32 v204, v149, v19
	v_mul_f32_e32 v216, v151, v21
	v_fmac_f32_e32 v204, v148, v18
	v_fmac_f32_e32 v216, v150, v20
	v_add_f32_e32 v204, v204, v216
	global_load_dwordx4 v[148:151], v[8:9], off nt
	v_lshl_add_u64 v[8:9], v[8:9], 0, s[6:7]
	s_waitcnt vmcnt(15)
	v_mul_f32_e32 v205, v153, v19
	v_mul_f32_e32 v216, v155, v21
	v_fmac_f32_e32 v205, v152, v18
	v_fmac_f32_e32 v216, v154, v20
	v_add_f32_e32 v205, v205, v216
	global_load_dwordx4 v[152:155], v[8:9], off nt
	v_lshl_add_u64 v[8:9], v[8:9], 0, s[6:7]
	s_waitcnt vmcnt(15)
	v_mul_f32_e32 v206, v157, v19
	v_mul_f32_e32 v216, v159, v21
	v_fmac_f32_e32 v206, v156, v18
	v_fmac_f32_e32 v216, v158, v20
	v_add_f32_e32 v206, v206, v216
	global_load_dwordx4 v[156:159], v[8:9], off nt
	v_lshl_add_u64 v[8:9], v[8:9], 0, s[6:7]
	s_waitcnt vmcnt(15)
	v_mul_f32_e32 v207, v161, v19
	v_mul_f32_e32 v216, v163, v21
	v_fmac_f32_e32 v207, v160, v18
	v_fmac_f32_e32 v216, v162, v20
	v_add_f32_e32 v207, v207, v216
	global_load_dwordx4 v[160:163], v[8:9], off nt
	v_lshl_add_u64 v[8:9], v[8:9], 0, s[6:7]
	s_waitcnt vmcnt(15)
	v_mul_f32_e32 v208, v165, v19
	v_mul_f32_e32 v216, v167, v21
	v_fmac_f32_e32 v208, v164, v18
	v_fmac_f32_e32 v216, v166, v20
	v_add_f32_e32 v208, v208, v216
	global_load_dwordx4 v[164:167], v[8:9], off nt
	v_lshl_add_u64 v[8:9], v[8:9], 0, s[6:7]
	s_waitcnt vmcnt(15)
	v_mul_f32_e32 v209, v169, v19
	v_mul_f32_e32 v216, v171, v21
	v_fmac_f32_e32 v209, v168, v18
	v_fmac_f32_e32 v216, v170, v20
	v_add_f32_e32 v209, v209, v216
	global_load_dwordx4 v[168:171], v[8:9], off nt
	v_lshl_add_u64 v[8:9], v[8:9], 0, s[6:7]
	s_waitcnt vmcnt(15)
	v_mul_f32_e32 v210, v173, v19
	v_mul_f32_e32 v216, v175, v21
	v_fmac_f32_e32 v210, v172, v18
	v_fmac_f32_e32 v216, v174, v20
	v_add_f32_e32 v210, v210, v216
	global_load_dwordx4 v[172:175], v[8:9], off nt
	v_lshl_add_u64 v[8:9], v[8:9], 0, s[6:7]
	s_waitcnt vmcnt(15)
	v_mul_f32_e32 v211, v177, v19
	v_mul_f32_e32 v216, v179, v21
	v_fmac_f32_e32 v211, v176, v18
	v_fmac_f32_e32 v216, v178, v20
	v_add_f32_e32 v211, v211, v216
	global_load_dwordx4 v[176:179], v[8:9], off nt
	v_lshl_add_u64 v[8:9], v[8:9], 0, s[6:7]
	s_waitcnt vmcnt(15)
	v_mul_f32_e32 v212, v181, v19
	v_mul_f32_e32 v216, v183, v21
	v_fmac_f32_e32 v212, v180, v18
	v_fmac_f32_e32 v216, v182, v20
	v_add_f32_e32 v212, v212, v216
	global_load_dwordx4 v[180:183], v[8:9], off nt
	v_lshl_add_u64 v[8:9], v[8:9], 0, s[6:7]
	s_waitcnt vmcnt(15)
	v_mul_f32_e32 v213, v185, v19
	v_mul_f32_e32 v216, v187, v21
	v_fmac_f32_e32 v213, v184, v18
	v_fmac_f32_e32 v216, v186, v20
	v_add_f32_e32 v213, v213, v216
	global_load_dwordx4 v[184:187], v[8:9], off nt
	v_lshl_add_u64 v[8:9], v[8:9], 0, s[6:7]
	s_waitcnt vmcnt(15)
	v_mul_f32_e32 v214, v189, v19
	v_mul_f32_e32 v216, v191, v21
	v_fmac_f32_e32 v214, v188, v18
	v_fmac_f32_e32 v216, v190, v20
	v_add_f32_e32 v214, v214, v216
	global_load_dwordx4 v[188:191], v[8:9], off nt
	v_lshl_add_u64 v[8:9], v[8:9], 0, s[6:7]
	s_waitcnt vmcnt(15)
	v_mul_f32_e32 v215, v193, v19
	v_mul_f32_e32 v216, v195, v21
	v_fmac_f32_e32 v215, v192, v18
	v_fmac_f32_e32 v216, v194, v20
	v_add_f32_e32 v215, v215, v216
	global_load_dwordx4 v[192:195], v[8:9], off nt
	s_waitcnt vmcnt(15)
	v_mul_f32_e32 v230, v133, v19
	v_mul_f32_e32 v216, v135, v21
	v_fmac_f32_e32 v230, v132, v18
	v_fmac_f32_e32 v216, v134, v20
	v_add_f32_e32 v230, v230, v216
	s_waitcnt vmcnt(14)
	v_mul_f32_e32 v231, v137, v19
	v_mul_f32_e32 v216, v139, v21
	v_fmac_f32_e32 v231, v136, v18
	v_fmac_f32_e32 v216, v138, v20
	v_add_f32_e32 v231, v231, v216
	s_waitcnt vmcnt(13)
	v_mul_f32_e32 v232, v141, v19
	v_mul_f32_e32 v216, v143, v21
	v_fmac_f32_e32 v232, v140, v18
	v_fmac_f32_e32 v216, v142, v20
	v_add_f32_e32 v232, v232, v216
	s_waitcnt vmcnt(12)
	v_mul_f32_e32 v233, v145, v19
	v_mul_f32_e32 v216, v147, v21
	v_fmac_f32_e32 v233, v144, v18
	v_fmac_f32_e32 v216, v146, v20
	v_add_f32_e32 v233, v233, v216
	s_waitcnt vmcnt(11)
	v_mul_f32_e32 v234, v149, v19
	v_mul_f32_e32 v216, v151, v21
	v_fmac_f32_e32 v234, v148, v18
	v_fmac_f32_e32 v216, v150, v20
	v_add_f32_e32 v234, v234, v216
	s_waitcnt vmcnt(10)
	v_mul_f32_e32 v235, v153, v19
	v_mul_f32_e32 v216, v155, v21
	v_fmac_f32_e32 v235, v152, v18
	v_fmac_f32_e32 v216, v154, v20
	v_add_f32_e32 v235, v235, v216
	s_waitcnt vmcnt(9)
	v_mul_f32_e32 v236, v157, v19
	v_mul_f32_e32 v216, v159, v21
	v_fmac_f32_e32 v236, v156, v18
	v_fmac_f32_e32 v216, v158, v20
	v_add_f32_e32 v236, v236, v216
	s_waitcnt vmcnt(8)
	v_mul_f32_e32 v237, v161, v19
	v_mul_f32_e32 v216, v163, v21
	v_fmac_f32_e32 v237, v160, v18
	v_fmac_f32_e32 v216, v162, v20
	v_add_f32_e32 v237, v237, v216
	s_waitcnt vmcnt(7)
	v_mul_f32_e32 v238, v165, v19
	v_mul_f32_e32 v216, v167, v21
	v_fmac_f32_e32 v238, v164, v18
	v_fmac_f32_e32 v216, v166, v20
	v_add_f32_e32 v238, v238, v216
	s_waitcnt vmcnt(6)
	v_mul_f32_e32 v239, v169, v19
	v_mul_f32_e32 v216, v171, v21
	v_fmac_f32_e32 v239, v168, v18
	v_fmac_f32_e32 v216, v170, v20
	v_add_f32_e32 v239, v239, v216
	s_waitcnt vmcnt(5)
	v_mul_f32_e32 v240, v173, v19
	v_mul_f32_e32 v216, v175, v21
	v_fmac_f32_e32 v240, v172, v18
	v_fmac_f32_e32 v216, v174, v20
	v_add_f32_e32 v240, v240, v216
	s_waitcnt vmcnt(4)
	v_mul_f32_e32 v241, v177, v19
	v_mul_f32_e32 v216, v179, v21
	v_fmac_f32_e32 v241, v176, v18
	v_fmac_f32_e32 v216, v178, v20
	v_add_f32_e32 v241, v241, v216
	s_waitcnt vmcnt(3)
	v_mul_f32_e32 v242, v181, v19
	v_mul_f32_e32 v216, v183, v21
	v_fmac_f32_e32 v242, v180, v18
	v_fmac_f32_e32 v216, v182, v20
	v_add_f32_e32 v242, v242, v216
	s_waitcnt vmcnt(2)
	v_mul_f32_e32 v243, v185, v19
	v_mul_f32_e32 v216, v187, v21
	v_fmac_f32_e32 v243, v184, v18
	v_fmac_f32_e32 v216, v186, v20
	v_add_f32_e32 v243, v243, v216
	s_waitcnt vmcnt(1)
	v_mul_f32_e32 v244, v189, v19
	v_mul_f32_e32 v216, v191, v21
	v_fmac_f32_e32 v244, v188, v18
	v_fmac_f32_e32 v216, v190, v20
	v_add_f32_e32 v244, v244, v216
	s_waitcnt vmcnt(0)
	v_mul_f32_e32 v245, v193, v19
	v_mul_f32_e32 v216, v195, v21
	v_fmac_f32_e32 v245, v192, v18
	v_fmac_f32_e32 v216, v194, v20
	v_add_f32_e32 v245, v245, v216
	s_nop 1
	v_add_f32_dpp v200, v200, v200 quad_perm:[1,0,3,2] row_mask:0xf bank_mask:0xf
	v_add_f32_dpp v201, v201, v201 quad_perm:[1,0,3,2] row_mask:0xf bank_mask:0xf
	v_add_f32_dpp v202, v202, v202 quad_perm:[1,0,3,2] row_mask:0xf bank_mask:0xf
	v_add_f32_dpp v203, v203, v203 quad_perm:[1,0,3,2] row_mask:0xf bank_mask:0xf
	v_add_f32_dpp v204, v204, v204 quad_perm:[1,0,3,2] row_mask:0xf bank_mask:0xf
	v_add_f32_dpp v205, v205, v205 quad_perm:[1,0,3,2] row_mask:0xf bank_mask:0xf
	v_add_f32_dpp v206, v206, v206 quad_perm:[1,0,3,2] row_mask:0xf bank_mask:0xf
	v_add_f32_dpp v207, v207, v207 quad_perm:[1,0,3,2] row_mask:0xf bank_mask:0xf
	v_add_f32_dpp v208, v208, v208 quad_perm:[1,0,3,2] row_mask:0xf bank_mask:0xf
	v_add_f32_dpp v209, v209, v209 quad_perm:[1,0,3,2] row_mask:0xf bank_mask:0xf
	v_add_f32_dpp v210, v210, v210 quad_perm:[1,0,3,2] row_mask:0xf bank_mask:0xf
	v_add_f32_dpp v211, v211, v211 quad_perm:[1,0,3,2] row_mask:0xf bank_mask:0xf
	v_add_f32_dpp v212, v212, v212 quad_perm:[1,0,3,2] row_mask:0xf bank_mask:0xf
	v_add_f32_dpp v213, v213, v213 quad_perm:[1,0,3,2] row_mask:0xf bank_mask:0xf
	v_add_f32_dpp v214, v214, v214 quad_perm:[1,0,3,2] row_mask:0xf bank_mask:0xf
	v_add_f32_dpp v215, v215, v215 quad_perm:[1,0,3,2] row_mask:0xf bank_mask:0xf
	v_add_f32_dpp v230, v230, v230 quad_perm:[1,0,3,2] row_mask:0xf bank_mask:0xf
	v_add_f32_dpp v231, v231, v231 quad_perm:[1,0,3,2] row_mask:0xf bank_mask:0xf
	v_add_f32_dpp v232, v232, v232 quad_perm:[1,0,3,2] row_mask:0xf bank_mask:0xf
	v_add_f32_dpp v233, v233, v233 quad_perm:[1,0,3,2] row_mask:0xf bank_mask:0xf
	v_add_f32_dpp v234, v234, v234 quad_perm:[1,0,3,2] row_mask:0xf bank_mask:0xf
	v_add_f32_dpp v235, v235, v235 quad_perm:[1,0,3,2] row_mask:0xf bank_mask:0xf
	v_add_f32_dpp v236, v236, v236 quad_perm:[1,0,3,2] row_mask:0xf bank_mask:0xf
	v_add_f32_dpp v237, v237, v237 quad_perm:[1,0,3,2] row_mask:0xf bank_mask:0xf
	v_add_f32_dpp v238, v238, v238 quad_perm:[1,0,3,2] row_mask:0xf bank_mask:0xf
	v_add_f32_dpp v239, v239, v239 quad_perm:[1,0,3,2] row_mask:0xf bank_mask:0xf
	v_add_f32_dpp v240, v240, v240 quad_perm:[1,0,3,2] row_mask:0xf bank_mask:0xf
	v_add_f32_dpp v241, v241, v241 quad_perm:[1,0,3,2] row_mask:0xf bank_mask:0xf
	v_add_f32_dpp v242, v242, v242 quad_perm:[1,0,3,2] row_mask:0xf bank_mask:0xf
	v_add_f32_dpp v243, v243, v243 quad_perm:[1,0,3,2] row_mask:0xf bank_mask:0xf
	v_add_f32_dpp v244, v244, v244 quad_perm:[1,0,3,2] row_mask:0xf bank_mask:0xf
	v_add_f32_dpp v245, v245, v245 quad_perm:[1,0,3,2] row_mask:0xf bank_mask:0xf
	v_add_f32_dpp v200, v200, v200 quad_perm:[2,3,0,1] row_mask:0xf bank_mask:0xf
	v_add_f32_dpp v201, v201, v201 quad_perm:[2,3,0,1] row_mask:0xf bank_mask:0xf
	v_add_f32_dpp v202, v202, v202 quad_perm:[2,3,0,1] row_mask:0xf bank_mask:0xf
	v_add_f32_dpp v203, v203, v203 quad_perm:[2,3,0,1] row_mask:0xf bank_mask:0xf
	v_add_f32_dpp v204, v204, v204 quad_perm:[2,3,0,1] row_mask:0xf bank_mask:0xf
	v_add_f32_dpp v205, v205, v205 quad_perm:[2,3,0,1] row_mask:0xf bank_mask:0xf
	v_add_f32_dpp v206, v206, v206 quad_perm:[2,3,0,1] row_mask:0xf bank_mask:0xf
	v_add_f32_dpp v207, v207, v207 quad_perm:[2,3,0,1] row_mask:0xf bank_mask:0xf
	v_add_f32_dpp v208, v208, v208 quad_perm:[2,3,0,1] row_mask:0xf bank_mask:0xf
	v_add_f32_dpp v209, v209, v209 quad_perm:[2,3,0,1] row_mask:0xf bank_mask:0xf
	v_add_f32_dpp v210, v210, v210 quad_perm:[2,3,0,1] row_mask:0xf bank_mask:0xf
	v_add_f32_dpp v211, v211, v211 quad_perm:[2,3,0,1] row_mask:0xf bank_mask:0xf
	v_add_f32_dpp v212, v212, v212 quad_perm:[2,3,0,1] row_mask:0xf bank_mask:0xf
	v_add_f32_dpp v213, v213, v213 quad_perm:[2,3,0,1] row_mask:0xf bank_mask:0xf
	v_add_f32_dpp v214, v214, v214 quad_perm:[2,3,0,1] row_mask:0xf bank_mask:0xf
	v_add_f32_dpp v215, v215, v215 quad_perm:[2,3,0,1] row_mask:0xf bank_mask:0xf
	v_add_f32_dpp v230, v230, v230 quad_perm:[2,3,0,1] row_mask:0xf bank_mask:0xf
	v_add_f32_dpp v231, v231, v231 quad_perm:[2,3,0,1] row_mask:0xf bank_mask:0xf
	v_add_f32_dpp v232, v232, v232 quad_perm:[2,3,0,1] row_mask:0xf bank_mask:0xf
	v_add_f32_dpp v233, v233, v233 quad_perm:[2,3,0,1] row_mask:0xf bank_mask:0xf
	v_add_f32_dpp v234, v234, v234 quad_perm:[2,3,0,1] row_mask:0xf bank_mask:0xf
	v_add_f32_dpp v235, v235, v235 quad_perm:[2,3,0,1] row_mask:0xf bank_mask:0xf
	v_add_f32_dpp v236, v236, v236 quad_perm:[2,3,0,1] row_mask:0xf bank_mask:0xf
	v_add_f32_dpp v237, v237, v237 quad_perm:[2,3,0,1] row_mask:0xf bank_mask:0xf
	v_add_f32_dpp v238, v238, v238 quad_perm:[2,3,0,1] row_mask:0xf bank_mask:0xf
	v_add_f32_dpp v239, v239, v239 quad_perm:[2,3,0,1] row_mask:0xf bank_mask:0xf
	v_add_f32_dpp v240, v240, v240 quad_perm:[2,3,0,1] row_mask:0xf bank_mask:0xf
	v_add_f32_dpp v241, v241, v241 quad_perm:[2,3,0,1] row_mask:0xf bank_mask:0xf
	v_add_f32_dpp v242, v242, v242 quad_perm:[2,3,0,1] row_mask:0xf bank_mask:0xf
	v_add_f32_dpp v243, v243, v243 quad_perm:[2,3,0,1] row_mask:0xf bank_mask:0xf
	v_add_f32_dpp v244, v244, v244 quad_perm:[2,3,0,1] row_mask:0xf bank_mask:0xf
	v_add_f32_dpp v245, v245, v245 quad_perm:[2,3,0,1] row_mask:0xf bank_mask:0xf
	v_add_f32_dpp v200, v200, v200 row_ror:4 row_mask:0xf bank_mask:0xf
	v_add_f32_dpp v201, v201, v201 row_ror:4 row_mask:0xf bank_mask:0xf
	v_add_f32_dpp v202, v202, v202 row_ror:4 row_mask:0xf bank_mask:0xf
	v_add_f32_dpp v203, v203, v203 row_ror:4 row_mask:0xf bank_mask:0xf
	v_add_f32_dpp v204, v204, v204 row_ror:4 row_mask:0xf bank_mask:0xf
	v_add_f32_dpp v205, v205, v205 row_ror:4 row_mask:0xf bank_mask:0xf
	v_add_f32_dpp v206, v206, v206 row_ror:4 row_mask:0xf bank_mask:0xf
	v_add_f32_dpp v207, v207, v207 row_ror:4 row_mask:0xf bank_mask:0xf
	v_add_f32_dpp v208, v208, v208 row_ror:4 row_mask:0xf bank_mask:0xf
	v_add_f32_dpp v209, v209, v209 row_ror:4 row_mask:0xf bank_mask:0xf
	v_add_f32_dpp v210, v210, v210 row_ror:4 row_mask:0xf bank_mask:0xf
	v_add_f32_dpp v211, v211, v211 row_ror:4 row_mask:0xf bank_mask:0xf
	v_add_f32_dpp v212, v212, v212 row_ror:4 row_mask:0xf bank_mask:0xf
	v_add_f32_dpp v213, v213, v213 row_ror:4 row_mask:0xf bank_mask:0xf
	v_add_f32_dpp v214, v214, v214 row_ror:4 row_mask:0xf bank_mask:0xf
	v_add_f32_dpp v215, v215, v215 row_ror:4 row_mask:0xf bank_mask:0xf
	v_add_f32_dpp v230, v230, v230 row_ror:4 row_mask:0xf bank_mask:0xf
	v_add_f32_dpp v231, v231, v231 row_ror:4 row_mask:0xf bank_mask:0xf
	v_add_f32_dpp v232, v232, v232 row_ror:4 row_mask:0xf bank_mask:0xf
	v_add_f32_dpp v233, v233, v233 row_ror:4 row_mask:0xf bank_mask:0xf
	v_add_f32_dpp v234, v234, v234 row_ror:4 row_mask:0xf bank_mask:0xf
	v_add_f32_dpp v235, v235, v235 row_ror:4 row_mask:0xf bank_mask:0xf
	v_add_f32_dpp v236, v236, v236 row_ror:4 row_mask:0xf bank_mask:0xf
	v_add_f32_dpp v237, v237, v237 row_ror:4 row_mask:0xf bank_mask:0xf
	v_add_f32_dpp v238, v238, v238 row_ror:4 row_mask:0xf bank_mask:0xf
	v_add_f32_dpp v239, v239, v239 row_ror:4 row_mask:0xf bank_mask:0xf
	v_add_f32_dpp v240, v240, v240 row_ror:4 row_mask:0xf bank_mask:0xf
	v_add_f32_dpp v241, v241, v241 row_ror:4 row_mask:0xf bank_mask:0xf
	v_add_f32_dpp v242, v242, v242 row_ror:4 row_mask:0xf bank_mask:0xf
	v_add_f32_dpp v243, v243, v243 row_ror:4 row_mask:0xf bank_mask:0xf
	v_add_f32_dpp v244, v244, v244 row_ror:4 row_mask:0xf bank_mask:0xf
	v_add_f32_dpp v245, v245, v245 row_ror:4 row_mask:0xf bank_mask:0xf
	v_add_f32_dpp v200, v200, v200 row_ror:8 row_mask:0xf bank_mask:0xf
	v_add_f32_dpp v201, v201, v201 row_ror:8 row_mask:0xf bank_mask:0xf
	v_add_f32_dpp v202, v202, v202 row_ror:8 row_mask:0xf bank_mask:0xf
	v_add_f32_dpp v203, v203, v203 row_ror:8 row_mask:0xf bank_mask:0xf
	v_add_f32_dpp v204, v204, v204 row_ror:8 row_mask:0xf bank_mask:0xf
	v_add_f32_dpp v205, v205, v205 row_ror:8 row_mask:0xf bank_mask:0xf
	v_add_f32_dpp v206, v206, v206 row_ror:8 row_mask:0xf bank_mask:0xf
	v_add_f32_dpp v207, v207, v207 row_ror:8 row_mask:0xf bank_mask:0xf
	v_add_f32_dpp v208, v208, v208 row_ror:8 row_mask:0xf bank_mask:0xf
	v_add_f32_dpp v209, v209, v209 row_ror:8 row_mask:0xf bank_mask:0xf
	v_add_f32_dpp v210, v210, v210 row_ror:8 row_mask:0xf bank_mask:0xf
	v_add_f32_dpp v211, v211, v211 row_ror:8 row_mask:0xf bank_mask:0xf
	v_add_f32_dpp v212, v212, v212 row_ror:8 row_mask:0xf bank_mask:0xf
	v_add_f32_dpp v213, v213, v213 row_ror:8 row_mask:0xf bank_mask:0xf
	v_add_f32_dpp v214, v214, v214 row_ror:8 row_mask:0xf bank_mask:0xf
	v_add_f32_dpp v215, v215, v215 row_ror:8 row_mask:0xf bank_mask:0xf
	v_add_f32_dpp v230, v230, v230 row_ror:8 row_mask:0xf bank_mask:0xf
	v_add_f32_dpp v231, v231, v231 row_ror:8 row_mask:0xf bank_mask:0xf
	v_add_f32_dpp v232, v232, v232 row_ror:8 row_mask:0xf bank_mask:0xf
	v_add_f32_dpp v233, v233, v233 row_ror:8 row_mask:0xf bank_mask:0xf
	v_add_f32_dpp v234, v234, v234 row_ror:8 row_mask:0xf bank_mask:0xf
	v_add_f32_dpp v235, v235, v235 row_ror:8 row_mask:0xf bank_mask:0xf
	v_add_f32_dpp v236, v236, v236 row_ror:8 row_mask:0xf bank_mask:0xf
	v_add_f32_dpp v237, v237, v237 row_ror:8 row_mask:0xf bank_mask:0xf
	v_add_f32_dpp v238, v238, v238 row_ror:8 row_mask:0xf bank_mask:0xf
	v_add_f32_dpp v239, v239, v239 row_ror:8 row_mask:0xf bank_mask:0xf
	v_add_f32_dpp v240, v240, v240 row_ror:8 row_mask:0xf bank_mask:0xf
	v_add_f32_dpp v241, v241, v241 row_ror:8 row_mask:0xf bank_mask:0xf
	v_add_f32_dpp v242, v242, v242 row_ror:8 row_mask:0xf bank_mask:0xf
	v_add_f32_dpp v243, v243, v243 row_ror:8 row_mask:0xf bank_mask:0xf
	v_add_f32_dpp v244, v244, v244 row_ror:8 row_mask:0xf bank_mask:0xf
	v_add_f32_dpp v245, v245, v245 row_ror:8 row_mask:0xf bank_mask:0xf
	s_and_saveexec_b64 s[2:3], vcc
	s_nop 0
	ds_write_b32 v11, v200 offset:0
	ds_write_b32 v11, v201 offset:32
	ds_write_b32 v11, v202 offset:64
	ds_write_b32 v11, v203 offset:96
	ds_write_b32 v11, v204 offset:128
	ds_write_b32 v11, v205 offset:160
	ds_write_b32 v11, v206 offset:192
	ds_write_b32 v11, v207 offset:224
	ds_write_b32 v11, v208 offset:256
	ds_write_b32 v11, v209 offset:288
	ds_write_b32 v11, v210 offset:320
	ds_write_b32 v11, v211 offset:352
	ds_write_b32 v11, v212 offset:384
	ds_write_b32 v11, v213 offset:416
	ds_write_b32 v11, v214 offset:448
	ds_write_b32 v11, v215 offset:480
	ds_write_b32 v11, v230 offset:512
	ds_write_b32 v11, v231 offset:544
	ds_write_b32 v11, v232 offset:576
	ds_write_b32 v11, v233 offset:608
	ds_write_b32 v11, v234 offset:640
	ds_write_b32 v11, v235 offset:672
	ds_write_b32 v11, v236 offset:704
	ds_write_b32 v11, v237 offset:736
	ds_write_b32 v11, v238 offset:768
	ds_write_b32 v11, v239 offset:800
	ds_write_b32 v11, v240 offset:832
	ds_write_b32 v11, v241 offset:864
	ds_write_b32 v11, v242 offset:896
	ds_write_b32 v11, v243 offset:928
	ds_write_b32 v11, v244 offset:960
	ds_write_b32 v11, v245 offset:992
	s_or_b64 exec, exec, s[2:3]

.LBB0_425:
	s_or_b64 exec, exec, s[0:1]
	s_add_i32 s94, s20, 0xfffffc80
	v_cmp_lt_u32_e32 vcc, 11, v7
	s_and_saveexec_b64 s[0:1], vcc
	s_cbranch_execz .LBB0_429
	s_lshl_b64 s[2:3], s[94:95], 16
	v_readlane_b32 s4, v254, 45
	v_readlane_b32 s5, v254, 46
	s_add_u32 s2, s2, s4
	s_addc_u32 s3, s3, s5
	s_lshl_b64 s[2:3], s[2:3], 2
	s_add_u32 s2, s10, s2
	s_addc_u32 s3, s11, s3
	v_lshlrev_b32_e32 v12, 8, v18
	v_mov_b32_e32 v13, v1
	v_lshl_add_u64 v[12:13], s[2:3], 0, v[12:13]
	v_mov_b32_e32 v7, v1
	v_lshl_add_u64 v[12:13], v[12:13], 0, v[6:7]
	v_lshlrev_b32_e32 v7, 2, v16
	s_add_i32 s2, 0, 0xc00
	v_add3_u32 v7, v14, v7, s2
	v_readlane_b32 s2, v254, 56
	v_lshlrev_b32_e32 v17, 2, v78
	v_readlane_b32 s3, v254, 57
	s_add_u32 s2, s10, s2
	v_readlane_b32 s4, v254, 55
	v_add_u32_e32 v14, 12, v16
	v_and_b32_e32 v21, 0x300, v17
	v_lshlrev_b32_e32 v17, 4, v78
	s_addc_u32 s3, s11, s3
	s_add_i32 s4, s21, s4
	s_mov_b32 s5, s95
	v_ashrrev_i32_e32 v15, 31, v14
	v_and_b32_e32 v23, 0xf0, v17
	v_ashrrev_i32_e32 v17, 31, v16
	v_add_u32_e32 v20, -4, v16
	s_lshl_b64 s[4:5], s[4:5], 18
	v_lshlrev_b64 v[14:15], 10, v[14:15]
	v_lshlrev_b64 v[16:17], 10, v[16:17]
	v_lshl_add_u64 v[14:15], s[4:5], 0, v[14:15]
	v_lshl_add_u64 v[16:17], s[4:5], 0, v[16:17]
	v_or3_b32 v14, v14, v21, v23
	v_or3_b32 v16, v16, v21, v23
	v_lshl_add_u64 v[14:15], s[2:3], 0, v[14:15]
	v_lshl_add_u64 v[16:17], s[2:3], 0, v[16:17]
	s_mov_b64 s[2:3], 0
	s_mov_b64 s[4:5], 0x4000
	s_mov_b64 s[4:5], 0x1000
	ds_read2_b32 v[200:201], v7 offset0:0 offset1:4
	ds_read2_b32 v[202:203], v7 offset0:8 offset1:12
	ds_read2_b32 v[204:205], v7 offset0:16 offset1:20
	ds_read2_b32 v[206:207], v7 offset0:24 offset1:28
	ds_read2_b32 v[208:209], v7 offset0:32 offset1:36
	ds_read2_b32 v[210:211], v7 offset0:40 offset1:44
	ds_read2_b32 v[212:213], v7 offset0:48 offset1:52
	ds_read2_b32 v[214:215], v7 offset0:56 offset1:60
	ds_read2_b32 v[230:231], v7 offset0:64 offset1:68
	ds_read2_b32 v[232:233], v7 offset0:72 offset1:76
	ds_read2_b32 v[234:235], v7 offset0:80 offset1:84
	ds_read2_b32 v[236:237], v7 offset0:88 offset1:92
	ds_read2_b32 v[238:239], v7 offset0:96 offset1:100
	ds_read2_b32 v[240:241], v7 offset0:104 offset1:108
	ds_read2_b32 v[242:243], v7 offset0:112 offset1:116
	ds_read2_b32 v[244:245], v7 offset0:120 offset1:124
	global_load_dwordx4 v[132:135], v[16:17], off nt
	v_lshl_add_u64 v[16:17], v[16:17], 0, s[4:5]
	global_load_dwordx4 v[136:139], v[16:17], off nt
	v_lshl_add_u64 v[16:17], v[16:17], 0, s[4:5]
	global_load_dwordx4 v[140:143], v[16:17], off nt
	v_lshl_add_u64 v[16:17], v[16:17], 0, s[4:5]
	global_load_dwordx4 v[144:147], v[16:17], off nt
	v_lshl_add_u64 v[16:17], v[16:17], 0, s[4:5]
	global_load_dwordx4 v[148:151], v[16:17], off nt
	v_lshl_add_u64 v[16:17], v[16:17], 0, s[4:5]
	global_load_dwordx4 v[152:155], v[16:17], off nt
	v_lshl_add_u64 v[16:17], v[16:17], 0, s[4:5]
	global_load_dwordx4 v[156:159], v[16:17], off nt
	v_lshl_add_u64 v[16:17], v[16:17], 0, s[4:5]
	global_load_dwordx4 v[160:163], v[16:17], off nt
	v_lshl_add_u64 v[16:17], v[16:17], 0, s[4:5]
	global_load_dwordx4 v[164:167], v[16:17], off nt
	v_lshl_add_u64 v[16:17], v[16:17], 0, s[4:5]
	global_load_dwordx4 v[168:171], v[16:17], off nt
	v_lshl_add_u64 v[16:17], v[16:17], 0, s[4:5]
	global_load_dwordx4 v[172:175], v[16:17], off nt
	v_lshl_add_u64 v[16:17], v[16:17], 0, s[4:5]
	global_load_dwordx4 v[176:179], v[16:17], off nt
	v_lshl_add_u64 v[16:17], v[16:17], 0, s[4:5]
	global_load_dwordx4 v[180:183], v[16:17], off nt
	v_lshl_add_u64 v[16:17], v[16:17], 0, s[4:5]
	global_load_dwordx4 v[184:187], v[16:17], off nt
	v_lshl_add_u64 v[16:17], v[16:17], 0, s[4:5]
	global_load_dwordx4 v[188:191], v[16:17], off nt
	v_lshl_add_u64 v[16:17], v[16:17], 0, s[4:5]
	global_load_dwordx4 v[192:195], v[16:17], off nt
	v_lshl_add_u64 v[16:17], v[16:17], 0, s[4:5]
	s_waitcnt vmcnt(15) lgkmcnt(0)
	v_fmac_f32_e32 v10, v132, v200
	v_fmac_f32_e32 v11, v133, v200
	v_fmac_f32_e32 v8, v134, v200
	v_fmac_f32_e32 v9, v135, v200
	global_load_dwordx4 v[132:135], v[16:17], off nt
	v_lshl_add_u64 v[16:17], v[16:17], 0, s[4:5]
	s_waitcnt vmcnt(15)
	v_fmac_f32_e32 v10, v136, v201
	v_fmac_f32_e32 v11, v137, v201
	v_fmac_f32_e32 v8, v138, v201
	v_fmac_f32_e32 v9, v139, v201
	global_load_dwordx4 v[136:139], v[16:17], off nt
	v_lshl_add_u64 v[16:17], v[16:17], 0, s[4:5]
	s_waitcnt vmcnt(15)
	v_fmac_f32_e32 v10, v140, v202
	v_fmac_f32_e32 v11, v141, v202
	v_fmac_f32_e32 v8, v142, v202
	v_fmac_f32_e32 v9, v143, v202
	global_load_dwordx4 v[140:143], v[16:17], off nt
	v_lshl_add_u64 v[16:17], v[16:17], 0, s[4:5]
	s_waitcnt vmcnt(15)
	v_fmac_f32_e32 v10, v144, v203
	v_fmac_f32_e32 v11, v145, v203
	v_fmac_f32_e32 v8, v146, v203
	v_fmac_f32_e32 v9, v147, v203
	global_load_dwordx4 v[144:147], v[16:17], off nt
	v_lshl_add_u64 v[16:17], v[16:17], 0, s[4:5]
	s_waitcnt vmcnt(15)
	v_fmac_f32_e32 v10, v148, v204
	v_fmac_f32_e32 v11, v149, v204
	v_fmac_f32_e32 v8, v150, v204
	v_fmac_f32_e32 v9, v151, v204
	global_load_dwordx4 v[148:151], v[16:17], off nt
	v_lshl_add_u64 v[16:17], v[16:17], 0, s[4:5]
	s_waitcnt vmcnt(15)
	v_fmac_f32_e32 v10, v152, v205
	v_fmac_f32_e32 v11, v153, v205
	v_fmac_f32_e32 v8, v154, v205
	v_fmac_f32_e32 v9, v155, v205
	global_load_dwordx4 v[152:155], v[16:17], off nt
	v_lshl_add_u64 v[16:17], v[16:17], 0, s[4:5]
	s_waitcnt vmcnt(15)
	v_fmac_f32_e32 v10, v156, v206
	v_fmac_f32_e32 v11, v157, v206
	v_fmac_f32_e32 v8, v158, v206
	v_fmac_f32_e32 v9, v159, v206
	global_load_dwordx4 v[156:159], v[16:17], off nt
	v_lshl_add_u64 v[16:17], v[16:17], 0, s[4:5]
	s_waitcnt vmcnt(15)
	v_fmac_f32_e32 v10, v160, v207
	v_fmac_f32_e32 v11, v161, v207
	v_fmac_f32_e32 v8, v162, v207
	v_fmac_f32_e32 v9, v163, v207
	global_load_dwordx4 v[160:163], v[16:17], off nt
	v_lshl_add_u64 v[16:17], v[16:17], 0, s[4:5]
	s_waitcnt vmcnt(15)
	v_fmac_f32_e32 v10, v164, v208
	v_fmac_f32_e32 v11, v165, v208
	v_fmac_f32_e32 v8, v166, v208
	v_fmac_f32_e32 v9, v167, v208
	global_load_dwordx4 v[164:167], v[16:17], off nt
	v_lshl_add_u64 v[16:17], v[16:17], 0, s[4:5]
	s_waitcnt vmcnt(15)
	v_fmac_f32_e32 v10, v168, v209
	v_fmac_f32_e32 v11, v169, v209
	v_fmac_f32_e32 v8, v170, v209
	v_fmac_f32_e32 v9, v171, v209
	global_load_dwordx4 v[168:171], v[16:17], off nt
	v_lshl_add_u64 v[16:17], v[16:17], 0, s[4:5]
	s_waitcnt vmcnt(15)
	v_fmac_f32_e32 v10, v172, v210
	v_fmac_f32_e32 v11, v173, v210
	v_fmac_f32_e32 v8, v174, v210
	v_fmac_f32_e32 v9, v175, v210
	global_load_dwordx4 v[172:175], v[16:17], off nt
	v_lshl_add_u64 v[16:17], v[16:17], 0, s[4:5]
	s_waitcnt vmcnt(15)
	v_fmac_f32_e32 v10, v176, v211
	v_fmac_f32_e32 v11, v177, v211
	v_fmac_f32_e32 v8, v178, v211
	v_fmac_f32_e32 v9, v179, v211
	global_load_dwordx4 v[176:179], v[16:17], off nt
	v_lshl_add_u64 v[16:17], v[16:17], 0, s[4:5]
	s_waitcnt vmcnt(15)
	v_fmac_f32_e32 v10, v180, v212
	v_fmac_f32_e32 v11, v181, v212
	v_fmac_f32_e32 v8, v182, v212
	v_fmac_f32_e32 v9, v183, v212
	global_load_dwordx4 v[180:183], v[16:17], off nt
	v_lshl_add_u64 v[16:17], v[16:17], 0, s[4:5]
	s_waitcnt vmcnt(15)
	v_fmac_f32_e32 v10, v184, v213
	v_fmac_f32_e32 v11, v185, v213
	v_fmac_f32_e32 v8, v186, v213
	v_fmac_f32_e32 v9, v187, v213
	global_load_dwordx4 v[184:187], v[16:17], off nt
	v_lshl_add_u64 v[16:17], v[16:17], 0, s[4:5]
	s_waitcnt vmcnt(15)
	v_fmac_f32_e32 v10, v188, v214
	v_fmac_f32_e32 v11, v189, v214
	v_fmac_f32_e32 v8, v190, v214
	v_fmac_f32_e32 v9, v191, v214
	global_load_dwordx4 v[188:191], v[16:17], off nt
	v_lshl_add_u64 v[16:17], v[16:17], 0, s[4:5]
	s_waitcnt vmcnt(15)
	v_fmac_f32_e32 v10, v192, v215
	v_fmac_f32_e32 v11, v193, v215
	v_fmac_f32_e32 v8, v194, v215
	v_fmac_f32_e32 v9, v195, v215
	global_load_dwordx4 v[192:195], v[16:17], off nt
	s_waitcnt vmcnt(15)
	v_fmac_f32_e32 v10, v132, v230
	v_fmac_f32_e32 v11, v133, v230
	v_fmac_f32_e32 v8, v134, v230
	v_fmac_f32_e32 v9, v135, v230
	s_waitcnt vmcnt(14)
	v_fmac_f32_e32 v10, v136, v231
	v_fmac_f32_e32 v11, v137, v231
	v_fmac_f32_e32 v8, v138, v231
	v_fmac_f32_e32 v9, v139, v231
	s_waitcnt vmcnt(13)
	v_fmac_f32_e32 v10, v140, v232
	v_fmac_f32_e32 v11, v141, v232
	v_fmac_f32_e32 v8, v142, v232
	v_fmac_f32_e32 v9, v143, v232
	s_waitcnt vmcnt(12)
	v_fmac_f32_e32 v10, v144, v233
	v_fmac_f32_e32 v11, v145, v233
	v_fmac_f32_e32 v8, v146, v233
	v_fmac_f32_e32 v9, v147, v233
	s_waitcnt vmcnt(11)
	v_fmac_f32_e32 v10, v148, v234
	v_fmac_f32_e32 v11, v149, v234
	v_fmac_f32_e32 v8, v150, v234
	v_fmac_f32_e32 v9, v151, v234
	s_waitcnt vmcnt(10)
	v_fmac_f32_e32 v10, v152, v235
	v_fmac_f32_e32 v11, v153, v235
	v_fmac_f32_e32 v8, v154, v235
	v_fmac_f32_e32 v9, v155, v235
	s_waitcnt vmcnt(9)
	v_fmac_f32_e32 v10, v156, v236
	v_fmac_f32_e32 v11, v157, v236
	v_fmac_f32_e32 v8, v158, v236
	v_fmac_f32_e32 v9, v159, v236
	s_waitcnt vmcnt(8)
	v_fmac_f32_e32 v10, v160, v237
	v_fmac_f32_e32 v11, v161, v237
	v_fmac_f32_e32 v8, v162, v237
	v_fmac_f32_e32 v9, v163, v237
	s_waitcnt vmcnt(7)
	v_fmac_f32_e32 v10, v164, v238
	v_fmac_f32_e32 v11, v165, v238
	v_fmac_f32_e32 v8, v166, v238
	v_fmac_f32_e32 v9, v167, v238
	s_waitcnt vmcnt(6)
	v_fmac_f32_e32 v10, v168, v239
	v_fmac_f32_e32 v11, v169, v239
	v_fmac_f32_e32 v8, v170, v239
	v_fmac_f32_e32 v9, v171, v239
	s_waitcnt vmcnt(5)
	v_fmac_f32_e32 v10, v172, v240
	v_fmac_f32_e32 v11, v173, v240
	v_fmac_f32_e32 v8, v174, v240
	v_fmac_f32_e32 v9, v175, v240
	s_waitcnt vmcnt(4)
	v_fmac_f32_e32 v10, v176, v241
	v_fmac_f32_e32 v11, v177, v241
	v_fmac_f32_e32 v8, v178, v241
	v_fmac_f32_e32 v9, v179, v241
	s_waitcnt vmcnt(3)
	v_fmac_f32_e32 v10, v180, v242
	v_fmac_f32_e32 v11, v181, v242
	v_fmac_f32_e32 v8, v182, v242
	v_fmac_f32_e32 v9, v183, v242
	s_waitcnt vmcnt(2)
	v_fmac_f32_e32 v10, v184, v243
	v_fmac_f32_e32 v11, v185, v243
	v_fmac_f32_e32 v8, v186, v243
	v_fmac_f32_e32 v9, v187, v243
	s_waitcnt vmcnt(1)
	v_fmac_f32_e32 v10, v188, v244
	v_fmac_f32_e32 v11, v189, v244
	v_fmac_f32_e32 v8, v190, v244
	v_fmac_f32_e32 v9, v191, v244
	s_waitcnt vmcnt(0)
	v_fmac_f32_e32 v10, v192, v245
	v_fmac_f32_e32 v11, v193, v245
	v_fmac_f32_e32 v8, v194, v245
	v_fmac_f32_e32 v9, v195, v245
	s_mov_b64 s[4:5], 0x4000
	s_or_b64 exec, exec, s[2:3]

.LBB0_447:
	s_or_b64 exec, exec, s[8:9]
	v_lshrrev_b32_e32 v18, 4, v22
	v_and_b32_e32 v13, 15, v78
	s_movk_i32 s6, 0x80
	v_cmp_gt_i32_e32 vcc, s6, v2
	v_mul_u32_u24_e32 v12, 3, v18
	v_lshl_add_u32 v23, v13, 4, 0
	s_waitcnt lgkmcnt(0)
	s_barrier
	s_and_saveexec_b64 s[8:9], vcc
	s_cbranch_execz .LBB0_487
	v_lshlrev_b32_e32 v6, 8, v12
	v_add_u32_e32 v9, 0x100, v6
	v_add_u32_e32 v19, 0x200, v6
	v_mul_u32_u24_e32 v6, 0x410, v12
	v_lshlrev_b32_e32 v7, 2, v2
	v_readlane_b32 s6, v254, 16
	v_mul_u32_u24_e32 v3, 0xc30, v18
	s_mov_b32 s7, s95
	v_add3_u32 v14, v6, v7, s6
	s_add_i32 s6, 0, 0xc00
	v_add3_u32 v15, v3, v7, s6
	v_readlane_b32 s6, v254, 58
	s_add_i32 s6, s21, s6
	v_ashrrev_i32_e32 v3, 31, v2
	s_lshl_b64 s[6:7], s[6:7], 17
	v_lshlrev_b64 v[6:7], 10, v[2:3]
	v_lshl_add_u64 v[6:7], s[6:7], 0, v[6:7]
	v_mul_u32_u24_e32 v8, 0x300, v18
	v_lshl_or_b32 v6, v22, 4, v6
	v_cmp_eq_u32_e32 vcc, 0, v13
	v_lshl_add_u64 v[10:11], s[2:3], 0, v[6:7]
	s_mov_b64 s[2:3], 0
	v_add_u32_e32 v3, v23, v8
	v_add_u32_e32 v17, v23, v9
	v_add_u32_e32 v19, v23, v19
	s_mov_b64 s[6:7], 0x2000
	ds_read_b128 v[24:27], v3
	ds_read_b128 v[200:203], v17
	ds_read_b128 v[204:207], v19
	global_load_dwordx4 v[132:135], v[10:11], off nt
	v_lshl_add_u64 v[10:11], v[10:11], 0, s[6:7]
	global_load_dwordx4 v[136:139], v[10:11], off nt
	v_lshl_add_u64 v[10:11], v[10:11], 0, s[6:7]
	global_load_dwordx4 v[140:143], v[10:11], off nt
	v_lshl_add_u64 v[10:11], v[10:11], 0, s[6:7]
	global_load_dwordx4 v[144:147], v[10:11], off nt
	v_lshl_add_u64 v[10:11], v[10:11], 0, s[6:7]
	global_load_dwordx4 v[148:151], v[10:11], off nt
	v_lshl_add_u64 v[10:11], v[10:11], 0, s[6:7]
	global_load_dwordx4 v[152:155], v[10:11], off nt
	v_lshl_add_u64 v[10:11], v[10:11], 0, s[6:7]
	global_load_dwordx4 v[156:159], v[10:11], off nt
	v_lshl_add_u64 v[10:11], v[10:11], 0, s[6:7]
	global_load_dwordx4 v[160:163], v[10:11], off nt
	v_lshl_add_u64 v[10:11], v[10:11], 0, s[6:7]
	global_load_dwordx4 v[164:167], v[10:11], off nt
	v_lshl_add_u64 v[10:11], v[10:11], 0, s[6:7]
	global_load_dwordx4 v[168:171], v[10:11], off nt
	v_lshl_add_u64 v[10:11], v[10:11], 0, s[6:7]
	global_load_dwordx4 v[172:175], v[10:11], off nt
	v_lshl_add_u64 v[10:11], v[10:11], 0, s[6:7]
	global_load_dwordx4 v[176:179], v[10:11], off nt
	v_lshl_add_u64 v[10:11], v[10:11], 0, s[6:7]
	global_load_dwordx4 v[180:183], v[10:11], off nt
	v_lshl_add_u64 v[10:11], v[10:11], 0, s[6:7]
	global_load_dwordx4 v[184:187], v[10:11], off nt
	v_lshl_add_u64 v[10:11], v[10:11], 0, s[6:7]
	global_load_dwordx4 v[188:191], v[10:11], off nt
	v_lshl_add_u64 v[10:11], v[10:11], 0, s[6:7]
	global_load_dwordx4 v[192:195], v[10:11], off nt
	s_waitcnt vmcnt(15) lgkmcnt(0)
	v_mul_f32_e32 v230, v133, v25
	v_mul_f32_e32 v216, v135, v27
	v_fmac_f32_e32 v230, v132, v24
	v_fmac_f32_e32 v216, v134, v26
	v_add_f32_e32 v230, v230, v216
	v_mul_f32_e32 v246, v133, v201
	v_mul_f32_e32 v216, v135, v203
	v_fmac_f32_e32 v246, v132, v200
	v_fmac_f32_e32 v216, v134, v202
	v_add_f32_e32 v246, v246, v216
	v_mul_f32_e32 v216, v135, v207
	v_mul_f32_e32 v133, v133, v205
	v_fmac_f32_e32 v133, v132, v204
	v_fmac_f32_e32 v216, v134, v206
	v_add_f32_e32 v135, v133, v216
	s_waitcnt vmcnt(14)
	v_mul_f32_e32 v231, v137, v25
	v_mul_f32_e32 v216, v139, v27
	v_fmac_f32_e32 v231, v136, v24
	v_fmac_f32_e32 v216, v138, v26
	v_add_f32_e32 v231, v231, v216
	v_mul_f32_e32 v247, v137, v201
	v_mul_f32_e32 v216, v139, v203
	v_fmac_f32_e32 v247, v136, v200
	v_fmac_f32_e32 v216, v138, v202
	v_add_f32_e32 v247, v247, v216
	v_mul_f32_e32 v216, v139, v207
	v_mul_f32_e32 v137, v137, v205
	v_fmac_f32_e32 v137, v136, v204
	v_fmac_f32_e32 v216, v138, v206
	v_add_f32_e32 v139, v137, v216
	s_waitcnt vmcnt(13)
	v_mul_f32_e32 v232, v141, v25
	v_mul_f32_e32 v216, v143, v27
	v_fmac_f32_e32 v232, v140, v24
	v_fmac_f32_e32 v216, v142, v26
	v_add_f32_e32 v232, v232, v216
	v_mul_f32_e32 v248, v141, v201
	v_mul_f32_e32 v216, v143, v203
	v_fmac_f32_e32 v248, v140, v200
	v_fmac_f32_e32 v216, v142, v202
	v_add_f32_e32 v248, v248, v216
	v_mul_f32_e32 v216, v143, v207
	v_mul_f32_e32 v141, v141, v205
	v_fmac_f32_e32 v141, v140, v204
	v_fmac_f32_e32 v216, v142, v206
	v_add_f32_e32 v143, v141, v216
	s_waitcnt vmcnt(12)
	v_mul_f32_e32 v233, v145, v25
	v_mul_f32_e32 v216, v147, v27
	v_fmac_f32_e32 v233, v144, v24
	v_fmac_f32_e32 v216, v146, v26
	v_add_f32_e32 v233, v233, v216
	v_mul_f32_e32 v249, v145, v201
	v_mul_f32_e32 v216, v147, v203
	v_fmac_f32_e32 v249, v144, v200
	v_fmac_f32_e32 v216, v146, v202
	v_add_f32_e32 v249, v249, v216
	v_mul_f32_e32 v216, v147, v207
	v_mul_f32_e32 v145, v145, v205
	v_fmac_f32_e32 v145, v144, v204
	v_fmac_f32_e32 v216, v146, v206
	v_add_f32_e32 v147, v145, v216
	s_waitcnt vmcnt(11)
	v_mul_f32_e32 v234, v149, v25
	v_mul_f32_e32 v216, v151, v27
	v_fmac_f32_e32 v234, v148, v24
	v_fmac_f32_e32 v216, v150, v26
	v_add_f32_e32 v234, v234, v216
	v_mul_f32_e32 v250, v149, v201
	v_mul_f32_e32 v216, v151, v203
	v_fmac_f32_e32 v250, v148, v200
	v_fmac_f32_e32 v216, v150, v202
	v_add_f32_e32 v250, v250, v216
	v_mul_f32_e32 v216, v151, v207
	v_mul_f32_e32 v149, v149, v205
	v_fmac_f32_e32 v149, v148, v204
	v_fmac_f32_e32 v216, v150, v206
	v_add_f32_e32 v151, v149, v216
	s_waitcnt vmcnt(10)
	v_mul_f32_e32 v235, v153, v25
	v_mul_f32_e32 v216, v155, v27
	v_fmac_f32_e32 v235, v152, v24
	v_fmac_f32_e32 v216, v154, v26
	v_add_f32_e32 v235, v235, v216
	v_mul_f32_e32 v251, v153, v201
	v_mul_f32_e32 v216, v155, v203
	v_fmac_f32_e32 v251, v152, v200
	v_fmac_f32_e32 v216, v154, v202
	v_add_f32_e32 v251, v251, v216
	v_mul_f32_e32 v216, v155, v207
	v_mul_f32_e32 v153, v153, v205
	v_fmac_f32_e32 v153, v152, v204
	v_fmac_f32_e32 v216, v154, v206
	v_add_f32_e32 v155, v153, v216
	s_waitcnt vmcnt(9)
	v_mul_f32_e32 v236, v157, v25
	v_mul_f32_e32 v216, v159, v27
	v_fmac_f32_e32 v236, v156, v24
	v_fmac_f32_e32 v216, v158, v26
	v_add_f32_e32 v236, v236, v216
	v_mul_f32_e32 v252, v157, v201
	v_mul_f32_e32 v216, v159, v203
	v_fmac_f32_e32 v252, v156, v200
	v_fmac_f32_e32 v216, v158, v202
	v_add_f32_e32 v252, v252, v216
	v_mul_f32_e32 v216, v159, v207
	v_mul_f32_e32 v157, v157, v205
	v_fmac_f32_e32 v157, v156, v204
	v_fmac_f32_e32 v216, v158, v206
	v_add_f32_e32 v159, v157, v216
	s_waitcnt vmcnt(8)
	v_mul_f32_e32 v237, v161, v25
	v_mul_f32_e32 v216, v163, v27
	v_fmac_f32_e32 v237, v160, v24
	v_fmac_f32_e32 v216, v162, v26
	v_add_f32_e32 v237, v237, v216
	v_mul_f32_e32 v253, v161, v201
	v_mul_f32_e32 v216, v163, v203
	v_fmac_f32_e32 v253, v160, v200
	v_fmac_f32_e32 v216, v162, v202
	v_add_f32_e32 v253, v253, v216
	v_mul_f32_e32 v216, v163, v207
	v_mul_f32_e32 v161, v161, v205
	v_fmac_f32_e32 v161, v160, v204
	v_fmac_f32_e32 v216, v162, v206
	v_add_f32_e32 v163, v161, v216
	s_waitcnt vmcnt(7)
	v_mul_f32_e32 v238, v165, v25
	v_mul_f32_e32 v216, v167, v27
	v_fmac_f32_e32 v238, v164, v24
	v_fmac_f32_e32 v216, v166, v26
	v_add_f32_e32 v238, v238, v216
	v_mul_f32_e32 v208, v165, v201
	v_mul_f32_e32 v216, v167, v203
	v_fmac_f32_e32 v208, v164, v200
	v_fmac_f32_e32 v216, v166, v202
	v_add_f32_e32 v208, v208, v216
	v_mul_f32_e32 v216, v167, v207
	v_mul_f32_e32 v165, v165, v205
	v_fmac_f32_e32 v165, v164, v204
	v_fmac_f32_e32 v216, v166, v206
	v_add_f32_e32 v167, v165, v216
	s_waitcnt vmcnt(6)
	v_mul_f32_e32 v239, v169, v25
	v_mul_f32_e32 v216, v171, v27
	v_fmac_f32_e32 v239, v168, v24
	v_fmac_f32_e32 v216, v170, v26
	v_add_f32_e32 v239, v239, v216
	v_mul_f32_e32 v209, v169, v201
	v_mul_f32_e32 v216, v171, v203
	v_fmac_f32_e32 v209, v168, v200
	v_fmac_f32_e32 v216, v170, v202
	v_add_f32_e32 v209, v209, v216
	v_mul_f32_e32 v216, v171, v207
	v_mul_f32_e32 v169, v169, v205
	v_fmac_f32_e32 v169, v168, v204
	v_fmac_f32_e32 v216, v170, v206
	v_add_f32_e32 v171, v169, v216
	s_waitcnt vmcnt(5)
	v_mul_f32_e32 v240, v173, v25
	v_mul_f32_e32 v216, v175, v27
	v_fmac_f32_e32 v240, v172, v24
	v_fmac_f32_e32 v216, v174, v26
	v_add_f32_e32 v240, v240, v216
	v_mul_f32_e32 v210, v173, v201
	v_mul_f32_e32 v216, v175, v203
	v_fmac_f32_e32 v210, v172, v200
	v_fmac_f32_e32 v216, v174, v202
	v_add_f32_e32 v210, v210, v216
	v_mul_f32_e32 v216, v175, v207
	v_mul_f32_e32 v173, v173, v205
	v_fmac_f32_e32 v173, v172, v204
	v_fmac_f32_e32 v216, v174, v206
	v_add_f32_e32 v175, v173, v216
	s_waitcnt vmcnt(4)
	v_mul_f32_e32 v241, v177, v25
	v_mul_f32_e32 v216, v179, v27
	v_fmac_f32_e32 v241, v176, v24
	v_fmac_f32_e32 v216, v178, v26
	v_add_f32_e32 v241, v241, v216
	v_mul_f32_e32 v211, v177, v201
	v_mul_f32_e32 v216, v179, v203
	v_fmac_f32_e32 v211, v176, v200
	v_fmac_f32_e32 v216, v178, v202
	v_add_f32_e32 v211, v211, v216
	v_mul_f32_e32 v216, v179, v207
	v_mul_f32_e32 v177, v177, v205
	v_fmac_f32_e32 v177, v176, v204
	v_fmac_f32_e32 v216, v178, v206
	v_add_f32_e32 v179, v177, v216
	s_waitcnt vmcnt(3)
	v_mul_f32_e32 v242, v181, v25
	v_mul_f32_e32 v216, v183, v27
	v_fmac_f32_e32 v242, v180, v24
	v_fmac_f32_e32 v216, v182, v26
	v_add_f32_e32 v242, v242, v216
	v_mul_f32_e32 v212, v181, v201
	v_mul_f32_e32 v216, v183, v203
	v_fmac_f32_e32 v212, v180, v200
	v_fmac_f32_e32 v216, v182, v202
	v_add_f32_e32 v212, v212, v216
	v_mul_f32_e32 v216, v183, v207
	v_mul_f32_e32 v181, v181, v205
	v_fmac_f32_e32 v181, v180, v204
	v_fmac_f32_e32 v216, v182, v206
	v_add_f32_e32 v183, v181, v216
	s_waitcnt vmcnt(2)
	v_mul_f32_e32 v243, v185, v25
	v_mul_f32_e32 v216, v187, v27
	v_fmac_f32_e32 v243, v184, v24
	v_fmac_f32_e32 v216, v186, v26
	v_add_f32_e32 v243, v243, v216
	v_mul_f32_e32 v213, v185, v201
	v_mul_f32_e32 v216, v187, v203
	v_fmac_f32_e32 v213, v184, v200
	v_fmac_f32_e32 v216, v186, v202
	v_add_f32_e32 v213, v213, v216
	v_mul_f32_e32 v216, v187, v207
	v_mul_f32_e32 v185, v185, v205
	v_fmac_f32_e32 v185, v184, v204
	v_fmac_f32_e32 v216, v186, v206
	v_add_f32_e32 v187, v185, v216
	s_waitcnt vmcnt(1)
	v_mul_f32_e32 v244, v189, v25
	v_mul_f32_e32 v216, v191, v27
	v_fmac_f32_e32 v244, v188, v24
	v_fmac_f32_e32 v216, v190, v26
	v_add_f32_e32 v244, v244, v216
	v_mul_f32_e32 v214, v189, v201
	v_mul_f32_e32 v216, v191, v203
	v_fmac_f32_e32 v214, v188, v200
	v_fmac_f32_e32 v216, v190, v202
	v_add_f32_e32 v214, v214, v216
	v_mul_f32_e32 v216, v191, v207
	v_mul_f32_e32 v189, v189, v205
	v_fmac_f32_e32 v189, v188, v204
	v_fmac_f32_e32 v216, v190, v206
	v_add_f32_e32 v191, v189, v216
	s_waitcnt vmcnt(0)
	v_mul_f32_e32 v245, v193, v25
	v_mul_f32_e32 v216, v195, v27
	v_fmac_f32_e32 v245, v192, v24
	v_fmac_f32_e32 v216, v194, v26
	v_add_f32_e32 v245, v245, v216
	v_mul_f32_e32 v215, v193, v201
	v_mul_f32_e32 v216, v195, v203
	v_fmac_f32_e32 v215, v192, v200
	v_fmac_f32_e32 v216, v194, v202
	v_add_f32_e32 v215, v215, v216
	v_mul_f32_e32 v216, v195, v207
	v_mul_f32_e32 v193, v193, v205
	v_fmac_f32_e32 v193, v192, v204
	v_fmac_f32_e32 v216, v194, v206
	v_add_f32_e32 v195, v193, v216
	s_nop 1
	v_add_f32_dpp v230, v230, v230 quad_perm:[1,0,3,2] row_mask:0xf bank_mask:0xf
	v_add_f32_dpp v231, v231, v231 quad_perm:[1,0,3,2] row_mask:0xf bank_mask:0xf
	v_add_f32_dpp v232, v232, v232 quad_perm:[1,0,3,2] row_mask:0xf bank_mask:0xf
	v_add_f32_dpp v233, v233, v233 quad_perm:[1,0,3,2] row_mask:0xf bank_mask:0xf
	v_add_f32_dpp v234, v234, v234 quad_perm:[1,0,3,2] row_mask:0xf bank_mask:0xf
	v_add_f32_dpp v235, v235, v235 quad_perm:[1,0,3,2] row_mask:0xf bank_mask:0xf
	v_add_f32_dpp v236, v236, v236 quad_perm:[1,0,3,2] row_mask:0xf bank_mask:0xf
	v_add_f32_dpp v237, v237, v237 quad_perm:[1,0,3,2] row_mask:0xf bank_mask:0xf
	v_add_f32_dpp v238, v238, v238 quad_perm:[1,0,3,2] row_mask:0xf bank_mask:0xf
	v_add_f32_dpp v239, v239, v239 quad_perm:[1,0,3,2] row_mask:0xf bank_mask:0xf
	v_add_f32_dpp v240, v240, v240 quad_perm:[1,0,3,2] row_mask:0xf bank_mask:0xf
	v_add_f32_dpp v241, v241, v241 quad_perm:[1,0,3,2] row_mask:0xf bank_mask:0xf
	v_add_f32_dpp v242, v242, v242 quad_perm:[1,0,3,2] row_mask:0xf bank_mask:0xf
	v_add_f32_dpp v243, v243, v243 quad_perm:[1,0,3,2] row_mask:0xf bank_mask:0xf
	v_add_f32_dpp v244, v244, v244 quad_perm:[1,0,3,2] row_mask:0xf bank_mask:0xf
	v_add_f32_dpp v245, v245, v245 quad_perm:[1,0,3,2] row_mask:0xf bank_mask:0xf
	v_add_f32_dpp v246, v246, v246 quad_perm:[1,0,3,2] row_mask:0xf bank_mask:0xf
	v_add_f32_dpp v247, v247, v247 quad_perm:[1,0,3,2] row_mask:0xf bank_mask:0xf
	v_add_f32_dpp v248, v248, v248 quad_perm:[1,0,3,2] row_mask:0xf bank_mask:0xf
	v_add_f32_dpp v249, v249, v249 quad_perm:[1,0,3,2] row_mask:0xf bank_mask:0xf
	v_add_f32_dpp v250, v250, v250 quad_perm:[1,0,3,2] row_mask:0xf bank_mask:0xf
	v_add_f32_dpp v251, v251, v251 quad_perm:[1,0,3,2] row_mask:0xf bank_mask:0xf
	v_add_f32_dpp v252, v252, v252 quad_perm:[1,0,3,2] row_mask:0xf bank_mask:0xf
	v_add_f32_dpp v253, v253, v253 quad_perm:[1,0,3,2] row_mask:0xf bank_mask:0xf
	v_add_f32_dpp v208, v208, v208 quad_perm:[1,0,3,2] row_mask:0xf bank_mask:0xf
	v_add_f32_dpp v209, v209, v209 quad_perm:[1,0,3,2] row_mask:0xf bank_mask:0xf
	v_add_f32_dpp v210, v210, v210 quad_perm:[1,0,3,2] row_mask:0xf bank_mask:0xf
	v_add_f32_dpp v211, v211, v211 quad_perm:[1,0,3,2] row_mask:0xf bank_mask:0xf
	v_add_f32_dpp v212, v212, v212 quad_perm:[1,0,3,2] row_mask:0xf bank_mask:0xf
	v_add_f32_dpp v213, v213, v213 quad_perm:[1,0,3,2] row_mask:0xf bank_mask:0xf
	v_add_f32_dpp v214, v214, v214 quad_perm:[1,0,3,2] row_mask:0xf bank_mask:0xf
	v_add_f32_dpp v215, v215, v215 quad_perm:[1,0,3,2] row_mask:0xf bank_mask:0xf
	v_add_f32_dpp v135, v135, v135 quad_perm:[1,0,3,2] row_mask:0xf bank_mask:0xf
	v_add_f32_dpp v139, v139, v139 quad_perm:[1,0,3,2] row_mask:0xf bank_mask:0xf
	v_add_f32_dpp v143, v143, v143 quad_perm:[1,0,3,2] row_mask:0xf bank_mask:0xf
	v_add_f32_dpp v147, v147, v147 quad_perm:[1,0,3,2] row_mask:0xf bank_mask:0xf
	v_add_f32_dpp v151, v151, v151 quad_perm:[1,0,3,2] row_mask:0xf bank_mask:0xf
	v_add_f32_dpp v155, v155, v155 quad_perm:[1,0,3,2] row_mask:0xf bank_mask:0xf
	v_add_f32_dpp v159, v159, v159 quad_perm:[1,0,3,2] row_mask:0xf bank_mask:0xf
	v_add_f32_dpp v163, v163, v163 quad_perm:[1,0,3,2] row_mask:0xf bank_mask:0xf
	v_add_f32_dpp v167, v167, v167 quad_perm:[1,0,3,2] row_mask:0xf bank_mask:0xf
	v_add_f32_dpp v171, v171, v171 quad_perm:[1,0,3,2] row_mask:0xf bank_mask:0xf
	v_add_f32_dpp v175, v175, v175 quad_perm:[1,0,3,2] row_mask:0xf bank_mask:0xf
	v_add_f32_dpp v179, v179, v179 quad_perm:[1,0,3,2] row_mask:0xf bank_mask:0xf
	v_add_f32_dpp v183, v183, v183 quad_perm:[1,0,3,2] row_mask:0xf bank_mask:0xf
	v_add_f32_dpp v187, v187, v187 quad_perm:[1,0,3,2] row_mask:0xf bank_mask:0xf
	v_add_f32_dpp v191, v191, v191 quad_perm:[1,0,3,2] row_mask:0xf bank_mask:0xf
	v_add_f32_dpp v195, v195, v195 quad_perm:[1,0,3,2] row_mask:0xf bank_mask:0xf
	v_add_f32_dpp v230, v230, v230 quad_perm:[2,3,0,1] row_mask:0xf bank_mask:0xf
	v_add_f32_dpp v231, v231, v231 quad_perm:[2,3,0,1] row_mask:0xf bank_mask:0xf
	v_add_f32_dpp v232, v232, v232 quad_perm:[2,3,0,1] row_mask:0xf bank_mask:0xf
	v_add_f32_dpp v233, v233, v233 quad_perm:[2,3,0,1] row_mask:0xf bank_mask:0xf
	v_add_f32_dpp v234, v234, v234 quad_perm:[2,3,0,1] row_mask:0xf bank_mask:0xf
	v_add_f32_dpp v235, v235, v235 quad_perm:[2,3,0,1] row_mask:0xf bank_mask:0xf
	v_add_f32_dpp v236, v236, v236 quad_perm:[2,3,0,1] row_mask:0xf bank_mask:0xf
	v_add_f32_dpp v237, v237, v237 quad_perm:[2,3,0,1] row_mask:0xf bank_mask:0xf
	v_add_f32_dpp v238, v238, v238 quad_perm:[2,3,0,1] row_mask:0xf bank_mask:0xf
	v_add_f32_dpp v239, v239, v239 quad_perm:[2,3,0,1] row_mask:0xf bank_mask:0xf
	v_add_f32_dpp v240, v240, v240 quad_perm:[2,3,0,1] row_mask:0xf bank_mask:0xf
	v_add_f32_dpp v241, v241, v241 quad_perm:[2,3,0,1] row_mask:0xf bank_mask:0xf
	v_add_f32_dpp v242, v242, v242 quad_perm:[2,3,0,1] row_mask:0xf bank_mask:0xf
	v_add_f32_dpp v243, v243, v243 quad_perm:[2,3,0,1] row_mask:0xf bank_mask:0xf
	v_add_f32_dpp v244, v244, v244 quad_perm:[2,3,0,1] row_mask:0xf bank_mask:0xf
	v_add_f32_dpp v245, v245, v245 quad_perm:[2,3,0,1] row_mask:0xf bank_mask:0xf
	v_add_f32_dpp v246, v246, v246 quad_perm:[2,3,0,1] row_mask:0xf bank_mask:0xf
	v_add_f32_dpp v247, v247, v247 quad_perm:[2,3,0,1] row_mask:0xf bank_mask:0xf
	v_add_f32_dpp v248, v248, v248 quad_perm:[2,3,0,1] row_mask:0xf bank_mask:0xf
	v_add_f32_dpp v249, v249, v249 quad_perm:[2,3,0,1] row_mask:0xf bank_mask:0xf
	v_add_f32_dpp v250, v250, v250 quad_perm:[2,3,0,1] row_mask:0xf bank_mask:0xf
	v_add_f32_dpp v251, v251, v251 quad_perm:[2,3,0,1] row_mask:0xf bank_mask:0xf
	v_add_f32_dpp v252, v252, v252 quad_perm:[2,3,0,1] row_mask:0xf bank_mask:0xf
	v_add_f32_dpp v253, v253, v253 quad_perm:[2,3,0,1] row_mask:0xf bank_mask:0xf
	v_add_f32_dpp v208, v208, v208 quad_perm:[2,3,0,1] row_mask:0xf bank_mask:0xf
	v_add_f32_dpp v209, v209, v209 quad_perm:[2,3,0,1] row_mask:0xf bank_mask:0xf
	v_add_f32_dpp v210, v210, v210 quad_perm:[2,3,0,1] row_mask:0xf bank_mask:0xf
	v_add_f32_dpp v211, v211, v211 quad_perm:[2,3,0,1] row_mask:0xf bank_mask:0xf
	v_add_f32_dpp v212, v212, v212 quad_perm:[2,3,0,1] row_mask:0xf bank_mask:0xf
	v_add_f32_dpp v213, v213, v213 quad_perm:[2,3,0,1] row_mask:0xf bank_mask:0xf
	v_add_f32_dpp v214, v214, v214 quad_perm:[2,3,0,1] row_mask:0xf bank_mask:0xf
	v_add_f32_dpp v215, v215, v215 quad_perm:[2,3,0,1] row_mask:0xf bank_mask:0xf
	v_add_f32_dpp v135, v135, v135 quad_perm:[2,3,0,1] row_mask:0xf bank_mask:0xf
	v_add_f32_dpp v139, v139, v139 quad_perm:[2,3,0,1] row_mask:0xf bank_mask:0xf
	v_add_f32_dpp v143, v143, v143 quad_perm:[2,3,0,1] row_mask:0xf bank_mask:0xf
	v_add_f32_dpp v147, v147, v147 quad_perm:[2,3,0,1] row_mask:0xf bank_mask:0xf
	v_add_f32_dpp v151, v151, v151 quad_perm:[2,3,0,1] row_mask:0xf bank_mask:0xf
	v_add_f32_dpp v155, v155, v155 quad_perm:[2,3,0,1] row_mask:0xf bank_mask:0xf
	v_add_f32_dpp v159, v159, v159 quad_perm:[2,3,0,1] row_mask:0xf bank_mask:0xf
	v_add_f32_dpp v163, v163, v163 quad_perm:[2,3,0,1] row_mask:0xf bank_mask:0xf
	v_add_f32_dpp v167, v167, v167 quad_perm:[2,3,0,1] row_mask:0xf bank_mask:0xf
	v_add_f32_dpp v171, v171, v171 quad_perm:[2,3,0,1] row_mask:0xf bank_mask:0xf
	v_add_f32_dpp v175, v175, v175 quad_perm:[2,3,0,1] row_mask:0xf bank_mask:0xf
	v_add_f32_dpp v179, v179, v179 quad_perm:[2,3,0,1] row_mask:0xf bank_mask:0xf
	v_add_f32_dpp v183, v183, v183 quad_perm:[2,3,0,1] row_mask:0xf bank_mask:0xf
	v_add_f32_dpp v187, v187, v187 quad_perm:[2,3,0,1] row_mask:0xf bank_mask:0xf
	v_add_f32_dpp v191, v191, v191 quad_perm:[2,3,0,1] row_mask:0xf bank_mask:0xf
	v_add_f32_dpp v195, v195, v195 quad_perm:[2,3,0,1] row_mask:0xf bank_mask:0xf
	v_add_f32_dpp v230, v230, v230 row_ror:4 row_mask:0xf bank_mask:0xf
	v_add_f32_dpp v231, v231, v231 row_ror:4 row_mask:0xf bank_mask:0xf
	v_add_f32_dpp v232, v232, v232 row_ror:4 row_mask:0xf bank_mask:0xf
	v_add_f32_dpp v233, v233, v233 row_ror:4 row_mask:0xf bank_mask:0xf
	v_add_f32_dpp v234, v234, v234 row_ror:4 row_mask:0xf bank_mask:0xf
	v_add_f32_dpp v235, v235, v235 row_ror:4 row_mask:0xf bank_mask:0xf
	v_add_f32_dpp v236, v236, v236 row_ror:4 row_mask:0xf bank_mask:0xf
	v_add_f32_dpp v237, v237, v237 row_ror:4 row_mask:0xf bank_mask:0xf
	v_add_f32_dpp v238, v238, v238 row_ror:4 row_mask:0xf bank_mask:0xf
	v_add_f32_dpp v239, v239, v239 row_ror:4 row_mask:0xf bank_mask:0xf
	v_add_f32_dpp v240, v240, v240 row_ror:4 row_mask:0xf bank_mask:0xf
	v_add_f32_dpp v241, v241, v241 row_ror:4 row_mask:0xf bank_mask:0xf
	v_add_f32_dpp v242, v242, v242 row_ror:4 row_mask:0xf bank_mask:0xf
	v_add_f32_dpp v243, v243, v243 row_ror:4 row_mask:0xf bank_mask:0xf
	v_add_f32_dpp v244, v244, v244 row_ror:4 row_mask:0xf bank_mask:0xf
	v_add_f32_dpp v245, v245, v245 row_ror:4 row_mask:0xf bank_mask:0xf
	v_add_f32_dpp v246, v246, v246 row_ror:4 row_mask:0xf bank_mask:0xf
	v_add_f32_dpp v247, v247, v247 row_ror:4 row_mask:0xf bank_mask:0xf
	v_add_f32_dpp v248, v248, v248 row_ror:4 row_mask:0xf bank_mask:0xf
	v_add_f32_dpp v249, v249, v249 row_ror:4 row_mask:0xf bank_mask:0xf
	v_add_f32_dpp v250, v250, v250 row_ror:4 row_mask:0xf bank_mask:0xf
	v_add_f32_dpp v251, v251, v251 row_ror:4 row_mask:0xf bank_mask:0xf
	v_add_f32_dpp v252, v252, v252 row_ror:4 row_mask:0xf bank_mask:0xf
	v_add_f32_dpp v253, v253, v253 row_ror:4 row_mask:0xf bank_mask:0xf
	v_add_f32_dpp v208, v208, v208 row_ror:4 row_mask:0xf bank_mask:0xf
	v_add_f32_dpp v209, v209, v209 row_ror:4 row_mask:0xf bank_mask:0xf
	v_add_f32_dpp v210, v210, v210 row_ror:4 row_mask:0xf bank_mask:0xf
	v_add_f32_dpp v211, v211, v211 row_ror:4 row_mask:0xf bank_mask:0xf
	v_add_f32_dpp v212, v212, v212 row_ror:4 row_mask:0xf bank_mask:0xf
	v_add_f32_dpp v213, v213, v213 row_ror:4 row_mask:0xf bank_mask:0xf
	v_add_f32_dpp v214, v214, v214 row_ror:4 row_mask:0xf bank_mask:0xf
	v_add_f32_dpp v215, v215, v215 row_ror:4 row_mask:0xf bank_mask:0xf
	v_add_f32_dpp v135, v135, v135 row_ror:4 row_mask:0xf bank_mask:0xf
	v_add_f32_dpp v139, v139, v139 row_ror:4 row_mask:0xf bank_mask:0xf
	v_add_f32_dpp v143, v143, v143 row_ror:4 row_mask:0xf bank_mask:0xf
	v_add_f32_dpp v147, v147, v147 row_ror:4 row_mask:0xf bank_mask:0xf
	v_add_f32_dpp v151, v151, v151 row_ror:4 row_mask:0xf bank_mask:0xf
	v_add_f32_dpp v155, v155, v155 row_ror:4 row_mask:0xf bank_mask:0xf
	v_add_f32_dpp v159, v159, v159 row_ror:4 row_mask:0xf bank_mask:0xf
	v_add_f32_dpp v163, v163, v163 row_ror:4 row_mask:0xf bank_mask:0xf
	v_add_f32_dpp v167, v167, v167 row_ror:4 row_mask:0xf bank_mask:0xf
	v_add_f32_dpp v171, v171, v171 row_ror:4 row_mask:0xf bank_mask:0xf
	v_add_f32_dpp v175, v175, v175 row_ror:4 row_mask:0xf bank_mask:0xf
	v_add_f32_dpp v179, v179, v179 row_ror:4 row_mask:0xf bank_mask:0xf
	v_add_f32_dpp v183, v183, v183 row_ror:4 row_mask:0xf bank_mask:0xf
	v_add_f32_dpp v187, v187, v187 row_ror:4 row_mask:0xf bank_mask:0xf
	v_add_f32_dpp v191, v191, v191 row_ror:4 row_mask:0xf bank_mask:0xf
	v_add_f32_dpp v195, v195, v195 row_ror:4 row_mask:0xf bank_mask:0xf
	v_add_f32_dpp v230, v230, v230 row_ror:8 row_mask:0xf bank_mask:0xf
	v_add_f32_dpp v231, v231, v231 row_ror:8 row_mask:0xf bank_mask:0xf
	v_add_f32_dpp v232, v232, v232 row_ror:8 row_mask:0xf bank_mask:0xf
	v_add_f32_dpp v233, v233, v233 row_ror:8 row_mask:0xf bank_mask:0xf
	v_add_f32_dpp v234, v234, v234 row_ror:8 row_mask:0xf bank_mask:0xf
	v_add_f32_dpp v235, v235, v235 row_ror:8 row_mask:0xf bank_mask:0xf
	v_add_f32_dpp v236, v236, v236 row_ror:8 row_mask:0xf bank_mask:0xf
	v_add_f32_dpp v237, v237, v237 row_ror:8 row_mask:0xf bank_mask:0xf
	v_add_f32_dpp v238, v238, v238 row_ror:8 row_mask:0xf bank_mask:0xf
	v_add_f32_dpp v239, v239, v239 row_ror:8 row_mask:0xf bank_mask:0xf
	v_add_f32_dpp v240, v240, v240 row_ror:8 row_mask:0xf bank_mask:0xf
	v_add_f32_dpp v241, v241, v241 row_ror:8 row_mask:0xf bank_mask:0xf
	v_add_f32_dpp v242, v242, v242 row_ror:8 row_mask:0xf bank_mask:0xf
	v_add_f32_dpp v243, v243, v243 row_ror:8 row_mask:0xf bank_mask:0xf
	v_add_f32_dpp v244, v244, v244 row_ror:8 row_mask:0xf bank_mask:0xf
	v_add_f32_dpp v245, v245, v245 row_ror:8 row_mask:0xf bank_mask:0xf
	v_add_f32_dpp v246, v246, v246 row_ror:8 row_mask:0xf bank_mask:0xf
	v_add_f32_dpp v247, v247, v247 row_ror:8 row_mask:0xf bank_mask:0xf
	v_add_f32_dpp v248, v248, v248 row_ror:8 row_mask:0xf bank_mask:0xf
	v_add_f32_dpp v249, v249, v249 row_ror:8 row_mask:0xf bank_mask:0xf
	v_add_f32_dpp v250, v250, v250 row_ror:8 row_mask:0xf bank_mask:0xf
	v_add_f32_dpp v251, v251, v251 row_ror:8 row_mask:0xf bank_mask:0xf
	v_add_f32_dpp v252, v252, v252 row_ror:8 row_mask:0xf bank_mask:0xf
	v_add_f32_dpp v253, v253, v253 row_ror:8 row_mask:0xf bank_mask:0xf
	v_add_f32_dpp v208, v208, v208 row_ror:8 row_mask:0xf bank_mask:0xf
	v_add_f32_dpp v209, v209, v209 row_ror:8 row_mask:0xf bank_mask:0xf
	v_add_f32_dpp v210, v210, v210 row_ror:8 row_mask:0xf bank_mask:0xf
	v_add_f32_dpp v211, v211, v211 row_ror:8 row_mask:0xf bank_mask:0xf
	v_add_f32_dpp v212, v212, v212 row_ror:8 row_mask:0xf bank_mask:0xf
	v_add_f32_dpp v213, v213, v213 row_ror:8 row_mask:0xf bank_mask:0xf
	v_add_f32_dpp v214, v214, v214 row_ror:8 row_mask:0xf bank_mask:0xf
	v_add_f32_dpp v215, v215, v215 row_ror:8 row_mask:0xf bank_mask:0xf
	v_add_f32_dpp v135, v135, v135 row_ror:8 row_mask:0xf bank_mask:0xf
	v_add_f32_dpp v139, v139, v139 row_ror:8 row_mask:0xf bank_mask:0xf
	v_add_f32_dpp v143, v143, v143 row_ror:8 row_mask:0xf bank_mask:0xf
	v_add_f32_dpp v147, v147, v147 row_ror:8 row_mask:0xf bank_mask:0xf
	v_add_f32_dpp v151, v151, v151 row_ror:8 row_mask:0xf bank_mask:0xf
	v_add_f32_dpp v155, v155, v155 row_ror:8 row_mask:0xf bank_mask:0xf
	v_add_f32_dpp v159, v159, v159 row_ror:8 row_mask:0xf bank_mask:0xf
	v_add_f32_dpp v163, v163, v163 row_ror:8 row_mask:0xf bank_mask:0xf
	v_add_f32_dpp v167, v167, v167 row_ror:8 row_mask:0xf bank_mask:0xf
	v_add_f32_dpp v171, v171, v171 row_ror:8 row_mask:0xf bank_mask:0xf
	v_add_f32_dpp v175, v175, v175 row_ror:8 row_mask:0xf bank_mask:0xf
	v_add_f32_dpp v179, v179, v179 row_ror:8 row_mask:0xf bank_mask:0xf
	v_add_f32_dpp v183, v183, v183 row_ror:8 row_mask:0xf bank_mask:0xf
	v_add_f32_dpp v187, v187, v187 row_ror:8 row_mask:0xf bank_mask:0xf
	v_add_f32_dpp v191, v191, v191 row_ror:8 row_mask:0xf bank_mask:0xf
	v_add_f32_dpp v195, v195, v195 row_ror:8 row_mask:0xf bank_mask:0xf
	s_and_saveexec_b64 s[2:3], vcc
	s_nop 0
	ds_write_b32 v15, v230 offset:0
	ds_write_b32 v15, v231 offset:32
	ds_write_b32 v15, v232 offset:64
	ds_write_b32 v15, v233 offset:96
	ds_write_b32 v15, v234 offset:128
	ds_write_b32 v15, v235 offset:160
	ds_write_b32 v15, v236 offset:192
	ds_write_b32 v15, v237 offset:224
	ds_write_b32 v15, v238 offset:256
	ds_write_b32 v15, v239 offset:288
	ds_write_b32 v15, v240 offset:320
	ds_write_b32 v15, v241 offset:352
	ds_write_b32 v15, v242 offset:384
	ds_write_b32 v15, v243 offset:416
	ds_write_b32 v15, v244 offset:448
	ds_write_b32 v15, v245 offset:480
	ds_write_b32 v14, v246 offset:0
	ds_write_b32 v14, v247 offset:32
	ds_write_b32 v14, v248 offset:64
	ds_write_b32 v14, v249 offset:96
	ds_write_b32 v14, v250 offset:128
	ds_write_b32 v14, v251 offset:160
	ds_write_b32 v14, v252 offset:192
	ds_write_b32 v14, v253 offset:224
	ds_write_b32 v14, v208 offset:256
	ds_write_b32 v14, v209 offset:288
	ds_write_b32 v14, v210 offset:320
	ds_write_b32 v14, v211 offset:352
	ds_write_b32 v14, v212 offset:384
	ds_write_b32 v14, v213 offset:416
	ds_write_b32 v14, v214 offset:448
	ds_write_b32 v14, v215 offset:480
	ds_write_b32 v14, v135 offset:1040
	ds_write_b32 v14, v139 offset:1072
	ds_write_b32 v14, v143 offset:1104
	ds_write_b32 v14, v147 offset:1136
	ds_write_b32 v14, v151 offset:1168
	ds_write_b32 v14, v155 offset:1200
	ds_write_b32 v14, v159 offset:1232
	ds_write_b32 v14, v163 offset:1264
	ds_write_b32 v14, v167 offset:1296
	ds_write_b32 v14, v171 offset:1328
	ds_write_b32 v14, v175 offset:1360
	ds_write_b32 v14, v179 offset:1392
	ds_write_b32 v14, v183 offset:1424
	ds_write_b32 v14, v187 offset:1456
	ds_write_b32 v14, v191 offset:1488
	ds_write_b32 v14, v195 offset:1520
	s_or_b64 exec, exec, s[2:3]
	s_branch .LBB0_487

.LBB0_458:
	v_readlane_b32 s0, v254, 4
	s_add_i32 s3, s20, 0xfffffe00
	s_lshr_b32 s3, s3, 6
	v_mov_b32_e32 v0, s0
	ds_read_b64 v[2:3], v0
	v_readlane_b32 s2, v254, 61
	s_lshl_b32 s4, s3, 2
	v_readlane_b32 s5, v254, 53
	s_bfe_u32 s2, s2, 0x20004
	s_add_i32 s4, s4, s5
	s_or_b32 s4, s4, s2
	s_ashr_i32 s5, s4, 31
	s_waitcnt lgkmcnt(0)
	v_readfirstlane_b32 s0, v2
	s_lshl_b64 s[4:5], s[4:5], 15
	v_readfirstlane_b32 s1, v3
	s_add_u32 s4, s0, s4
	v_lshlrev_b32_e32 v6, 4, v78
	s_addc_u32 s5, s1, s5
	v_and_b32_e32 v0, 0x70, v6
	v_lshl_add_u64 v[2:3], s[4:5], 0, v[0:1]
	v_add_u32_e32 v10, 0, v0
	v_and_b32_e32 v0, 0x1f0, v6
	v_lshl_add_u64 v[6:7], s[4:5], 0, v[0:1]
	s_mov_b64 s[4:5], 0x9600000
	v_ashrrev_i32_e32 v11, 3, v78
	s_mov_b64 s[6:7], 0x9400000
	v_lshl_add_u64 v[12:13], v[6:7], 0, s[4:5]
	v_lshlrev_b32_e32 v6, 6, v11
	v_lshl_add_u64 v[2:3], v[2:3], 0, s[6:7]
	v_ashrrev_i32_e32 v7, 31, v6
	v_lshl_add_u64 v[6:7], v[6:7], 1, v[2:3]
	global_load_dwordx4 v[132:135], v[6:7], off
	v_mad_u64_u32 v[14:15], s[4:5], v11, s88, v[10:11]
	v_ashrrev_i32_e32 v11, 5, v78
	v_add_u32_e32 v0, 0, v0
	s_movk_i32 s6, 0x210
	v_readlane_b32 s12, v254, 47
	s_mov_b32 s8, 0xa000000
	v_readlane_b32 s9, v254, 35
	s_mov_b64 s[10:11], 0xa000600
	v_readlane_b32 s13, v254, 48
	v_readlane_b32 s14, v254, 54
	v_mov_b32_e32 v164, v14
	v_lshlrev_b32_e32 v6, 8, v11
	v_ashrrev_i32_e32 v7, 31, v6
	v_lshl_add_u64 v[6:7], v[6:7], 1, v[12:13]
	global_load_dwordx4 v[136:139], v[6:7], off
	v_mad_u64_u32 v[14:15], s[4:5], v11, s6, v[0:1]
	v_add_u32_e32 v11, 0x200, v78
	v_mov_b32_e32 v165, v14
	v_ashrrev_i32_e32 v14, 3, v11
	v_lshlrev_b32_e32 v6, 6, v14
	v_ashrrev_i32_e32 v7, 31, v6
	v_lshl_add_u64 v[6:7], v[6:7], 1, v[2:3]
	global_load_dwordx4 v[140:143], v[6:7], off
	v_mad_u64_u32 v[14:15], s[4:5], v14, s88, v[10:11]
	v_ashrrev_i32_e32 v11, 5, v11
	v_mov_b32_e32 v166, v14
	v_lshlrev_b32_e32 v6, 8, v11
	v_ashrrev_i32_e32 v7, 31, v6
	v_lshl_add_u64 v[6:7], v[6:7], 1, v[12:13]
	global_load_dwordx4 v[144:147], v[6:7], off
	v_mad_u64_u32 v[14:15], s[4:5], v11, s6, v[0:1]
	v_add_u32_e32 v11, 0x400, v78
	v_mov_b32_e32 v167, v14
	v_ashrrev_i32_e32 v14, 3, v11
	v_lshlrev_b32_e32 v6, 6, v14
	v_ashrrev_i32_e32 v7, 31, v6
	v_lshl_add_u64 v[6:7], v[6:7], 1, v[2:3]
	global_load_dwordx4 v[148:151], v[6:7], off
	v_mad_u64_u32 v[14:15], s[4:5], v14, s88, v[10:11]
	v_ashrrev_i32_e32 v11, 5, v11
	v_mov_b32_e32 v168, v14
	v_lshlrev_b32_e32 v6, 8, v11
	v_ashrrev_i32_e32 v7, 31, v6
	v_lshl_add_u64 v[6:7], v[6:7], 1, v[12:13]
	global_load_dwordx4 v[152:155], v[6:7], off
	v_mad_u64_u32 v[14:15], s[4:5], v11, s6, v[0:1]
	v_add_u32_e32 v11, 0x600, v78
	v_mov_b32_e32 v169, v14
	v_ashrrev_i32_e32 v14, 3, v11
	v_lshlrev_b32_e32 v6, 6, v14
	v_ashrrev_i32_e32 v7, 31, v6
	v_lshl_add_u64 v[2:3], v[6:7], 1, v[2:3]
	global_load_dwordx4 v[156:159], v[2:3], off
	v_mad_u64_u32 v[2:3], s[4:5], v14, s88, v[10:11]
	v_ashrrev_i32_e32 v10, 5, v11
	v_mov_b32_e32 v170, v2
	v_lshlrev_b32_e32 v2, 8, v10
	v_ashrrev_i32_e32 v3, 31, v2
	v_lshl_add_u64 v[2:3], v[2:3], 1, v[12:13]
	global_load_dwordx4 v[160:163], v[2:3], off
	v_mad_u64_u32 v[2:3], s[4:5], v10, s6, v[0:1]
	s_lshl_b32 s4, s20, 8
	s_and_b32 s4, s4, 0xf00
	s_lshl_b32 s5, s3, 12
	v_readlane_b32 s3, v254, 59
	s_add_u32 s3, s0, s3
	s_addc_u32 s6, s1, 0
	s_lshl_b32 s7, s2, 6
	s_lshl_b32 s2, s2, 7
	v_ashrrev_i32_e32 v0, 2, v78
	s_add_u32 s2, s3, s2
	s_addc_u32 s3, s6, 0
	s_lshl_b32 s94, s7, 1
	v_mov_b32_e32 v171, v2
	s_waitcnt vmcnt(7)
	ds_write_b128 v164, v[132:135]
	s_waitcnt vmcnt(6)
	ds_write_b128 v165, v[136:139] offset:36864
	s_waitcnt vmcnt(5)
	ds_write_b128 v166, v[140:143]
	s_waitcnt vmcnt(4)
	ds_write_b128 v167, v[144:147] offset:36864
	s_waitcnt vmcnt(3)
	ds_write_b128 v168, v[148:151]
	s_waitcnt vmcnt(2)
	ds_write_b128 v169, v[152:155] offset:36864
	s_waitcnt vmcnt(1)
	ds_write_b128 v170, v[156:159]
	s_waitcnt vmcnt(0)
	ds_write_b128 v171, v[160:163] offset:36864
	v_bfe_u32 v8, v78, 4, 2
	v_and_b32_e32 v9, -16, v0
	v_lshlrev_b32_e32 v0, 4, v8
	v_lshl_add_u64 v[2:3], s[2:3], 0, v[0:1]
	s_mov_b64 s[2:3], 0xc400000
	v_and_b32_e32 v7, 15, v78
	v_lshlrev_b32_e32 v6, 3, v8
	v_lshl_add_u64 v[2:3], v[2:3], 0, s[2:3]
	v_add_u32_e32 v10, 0, v0
	s_or_b32 s2, s5, s4
	v_mul_u32_u24_e32 v11, 0x90, v7
	v_sub_u32_e32 v12, v10, v6
	v_mul_u32_u24_e32 v13, 0x210, v7
	v_lshlrev_b32_e32 v8, 2, v8
	v_or_b32_e32 v0, s2, v7
	v_add_u32_e32 v30, v0, v9
	s_mov_b32 s4, 0
	s_mov_b64 s[2:3], -1
	v_lshlrev_b32_e32 v0, 2, v6
	v_add_u32_e32 v31, v10, v11
	v_add_u32_e32 v32, v12, v13
	v_lshlrev_b32_e32 v26, 1, v8
	s_waitcnt lgkmcnt(0)
	s_barrier

.LBB0_507:
	s_or_b64 exec, exec, s[2:3]
	v_cmp_lt_u32_e32 vcc, 11, v0
	s_and_saveexec_b64 s[2:3], vcc
	s_cbranch_execz .LBB0_511
	s_lshl_b64 s[4:5], s[94:95], 17
	s_add_u32 s4, s0, s4
	s_addc_u32 s5, s1, s5
	v_lshlrev_b32_e32 v0, 8, v25
	v_lshl_add_u64 v[18:19], s[4:5], 0, v[0:1]
	v_mov_b32_e32 v11, v1
	v_lshl_add_u64 v[18:19], v[18:19], 0, v[10:11]
	v_lshlrev_b32_e32 v11, 2, v20
	s_add_i32 s4, 0, 0xc00
	v_or_b32_e32 v0, 48, v26
	v_add3_u32 v26, v27, v11, s4
	v_readlane_b32 s4, v254, 58
	s_add_i32 s4, s21, s4
	s_mov_b32 s5, s95
	v_ashrrev_i32_e32 v21, 31, v20
	v_add_u32_e32 v27, -16, v20
	s_lshl_b64 s[4:5], s[4:5], 17
	v_lshlrev_b64 v[20:21], 10, v[20:21]
	v_lshl_add_u64 v[20:21], s[4:5], 0, v[20:21]
	v_or3_b32 v20, v20, v28, v10
	v_lshl_add_u64 v[10:11], s[0:1], 0, v[20:21]
	s_mov_b64 s[0:1], 0
	s_mov_b64 s[4:5], 0x4000
	s_mov_b64 s[4:5], 0x1000
	v_add_u32_e32 v216, 0x410, v26
	v_add_u32_e32 v217, 0x820, v26
	global_load_dwordx4 v[132:135], v[10:11], off nt
	v_lshl_add_u64 v[10:11], v[10:11], 0, s[4:5]
	global_load_dwordx4 v[136:139], v[10:11], off nt
	v_lshl_add_u64 v[10:11], v[10:11], 0, s[4:5]
	global_load_dwordx4 v[140:143], v[10:11], off nt
	v_lshl_add_u64 v[10:11], v[10:11], 0, s[4:5]
	global_load_dwordx4 v[144:147], v[10:11], off nt
	v_lshl_add_u64 v[10:11], v[10:11], 0, s[4:5]
	global_load_dwordx4 v[148:151], v[10:11], off nt
	v_lshl_add_u64 v[10:11], v[10:11], 0, s[4:5]
	global_load_dwordx4 v[152:155], v[10:11], off nt
	v_lshl_add_u64 v[10:11], v[10:11], 0, s[4:5]
	global_load_dwordx4 v[156:159], v[10:11], off nt
	v_lshl_add_u64 v[10:11], v[10:11], 0, s[4:5]
	global_load_dwordx4 v[160:163], v[10:11], off nt
	v_lshl_add_u64 v[10:11], v[10:11], 0, s[4:5]
	ds_read2_b32 v[164:165], v26 offset0:0 offset1:4
	ds_read2_b32 v[166:167], v26 offset0:8 offset1:12
	ds_read2_b32 v[168:169], v26 offset0:16 offset1:20
	ds_read2_b32 v[170:171], v26 offset0:24 offset1:28
	ds_read2_b32 v[172:173], v26 offset0:32 offset1:36
	ds_read2_b32 v[174:175], v26 offset0:40 offset1:44
	ds_read2_b32 v[176:177], v26 offset0:48 offset1:52
	ds_read2_b32 v[178:179], v26 offset0:56 offset1:60
	ds_read2_b32 v[180:181], v216 offset0:0 offset1:4
	ds_read2_b32 v[182:183], v216 offset0:8 offset1:12
	ds_read2_b32 v[184:185], v216 offset0:16 offset1:20
	ds_read2_b32 v[186:187], v216 offset0:24 offset1:28
	ds_read2_b32 v[188:189], v216 offset0:32 offset1:36
	ds_read2_b32 v[190:191], v216 offset0:40 offset1:44
	ds_read2_b32 v[192:193], v216 offset0:48 offset1:52
	ds_read2_b32 v[194:195], v216 offset0:56 offset1:60
	ds_read2_b32 v[200:201], v217 offset0:0 offset1:4
	ds_read2_b32 v[202:203], v217 offset0:8 offset1:12
	ds_read2_b32 v[204:205], v217 offset0:16 offset1:20
	ds_read2_b32 v[206:207], v217 offset0:24 offset1:28
	ds_read2_b32 v[208:209], v217 offset0:32 offset1:36
	ds_read2_b32 v[210:211], v217 offset0:40 offset1:44
	ds_read2_b32 v[212:213], v217 offset0:48 offset1:52
	ds_read2_b32 v[214:215], v217 offset0:56 offset1:60
	s_waitcnt vmcnt(7) lgkmcnt(0)
	v_fmac_f32_e32 v16, v132, v164
	v_fmac_f32_e32 v17, v133, v164
	v_fmac_f32_e32 v14, v134, v164
	v_fmac_f32_e32 v15, v135, v164
	v_fmac_f32_e32 v12, v132, v180
	v_fmac_f32_e32 v13, v133, v180
	v_fmac_f32_e32 v8, v134, v180
	v_fmac_f32_e32 v9, v135, v180
	v_fmac_f32_e32 v6, v132, v200
	v_fmac_f32_e32 v7, v133, v200
	v_fmac_f32_e32 v2, v134, v200
	v_fmac_f32_e32 v3, v135, v200
	global_load_dwordx4 v[132:135], v[10:11], off nt
	v_lshl_add_u64 v[10:11], v[10:11], 0, s[4:5]
	s_waitcnt vmcnt(7)
	v_fmac_f32_e32 v16, v136, v165
	v_fmac_f32_e32 v17, v137, v165
	v_fmac_f32_e32 v14, v138, v165
	v_fmac_f32_e32 v15, v139, v165
	v_fmac_f32_e32 v12, v136, v181
	v_fmac_f32_e32 v13, v137, v181
	v_fmac_f32_e32 v8, v138, v181
	v_fmac_f32_e32 v9, v139, v181
	v_fmac_f32_e32 v6, v136, v201
	v_fmac_f32_e32 v7, v137, v201
	v_fmac_f32_e32 v2, v138, v201
	v_fmac_f32_e32 v3, v139, v201
	global_load_dwordx4 v[136:139], v[10:11], off nt
	v_lshl_add_u64 v[10:11], v[10:11], 0, s[4:5]
	s_waitcnt vmcnt(7)
	v_fmac_f32_e32 v16, v140, v166
	v_fmac_f32_e32 v17, v141, v166
	v_fmac_f32_e32 v14, v142, v166
	v_fmac_f32_e32 v15, v143, v166
	v_fmac_f32_e32 v12, v140, v182
	v_fmac_f32_e32 v13, v141, v182
	v_fmac_f32_e32 v8, v142, v182
	v_fmac_f32_e32 v9, v143, v182
	v_fmac_f32_e32 v6, v140, v202
	v_fmac_f32_e32 v7, v141, v202
	v_fmac_f32_e32 v2, v142, v202
	v_fmac_f32_e32 v3, v143, v202
	global_load_dwordx4 v[140:143], v[10:11], off nt
	v_lshl_add_u64 v[10:11], v[10:11], 0, s[4:5]
	s_waitcnt vmcnt(7)
	v_fmac_f32_e32 v16, v144, v167
	v_fmac_f32_e32 v17, v145, v167
	v_fmac_f32_e32 v14, v146, v167
	v_fmac_f32_e32 v15, v147, v167
	v_fmac_f32_e32 v12, v144, v183
	v_fmac_f32_e32 v13, v145, v183
	v_fmac_f32_e32 v8, v146, v183
	v_fmac_f32_e32 v9, v147, v183
	v_fmac_f32_e32 v6, v144, v203
	v_fmac_f32_e32 v7, v145, v203
	v_fmac_f32_e32 v2, v146, v203
	v_fmac_f32_e32 v3, v147, v203
	global_load_dwordx4 v[144:147], v[10:11], off nt
	v_lshl_add_u64 v[10:11], v[10:11], 0, s[4:5]
	s_waitcnt vmcnt(7)
	v_fmac_f32_e32 v16, v148, v168
	v_fmac_f32_e32 v17, v149, v168
	v_fmac_f32_e32 v14, v150, v168
	v_fmac_f32_e32 v15, v151, v168
	v_fmac_f32_e32 v12, v148, v184
	v_fmac_f32_e32 v13, v149, v184
	v_fmac_f32_e32 v8, v150, v184
	v_fmac_f32_e32 v9, v151, v184
	v_fmac_f32_e32 v6, v148, v204
	v_fmac_f32_e32 v7, v149, v204
	v_fmac_f32_e32 v2, v150, v204
	v_fmac_f32_e32 v3, v151, v204
	global_load_dwordx4 v[148:151], v[10:11], off nt
	v_lshl_add_u64 v[10:11], v[10:11], 0, s[4:5]
	s_waitcnt vmcnt(7)
	v_fmac_f32_e32 v16, v152, v169
	v_fmac_f32_e32 v17, v153, v169
	v_fmac_f32_e32 v14, v154, v169
	v_fmac_f32_e32 v15, v155, v169
	v_fmac_f32_e32 v12, v152, v185
	v_fmac_f32_e32 v13, v153, v185
	v_fmac_f32_e32 v8, v154, v185
	v_fmac_f32_e32 v9, v155, v185
	v_fmac_f32_e32 v6, v152, v205
	v_fmac_f32_e32 v7, v153, v205
	v_fmac_f32_e32 v2, v154, v205
	v_fmac_f32_e32 v3, v155, v205
	global_load_dwordx4 v[152:155], v[10:11], off nt
	v_lshl_add_u64 v[10:11], v[10:11], 0, s[4:5]
	s_waitcnt vmcnt(7)
	v_fmac_f32_e32 v16, v156, v170
	v_fmac_f32_e32 v17, v157, v170
	v_fmac_f32_e32 v14, v158, v170
	v_fmac_f32_e32 v15, v159, v170
	v_fmac_f32_e32 v12, v156, v186
	v_fmac_f32_e32 v13, v157, v186
	v_fmac_f32_e32 v8, v158, v186
	v_fmac_f32_e32 v9, v159, v186
	v_fmac_f32_e32 v6, v156, v206
	v_fmac_f32_e32 v7, v157, v206
	v_fmac_f32_e32 v2, v158, v206
	v_fmac_f32_e32 v3, v159, v206
	global_load_dwordx4 v[156:159], v[10:11], off nt
	v_lshl_add_u64 v[10:11], v[10:11], 0, s[4:5]
	s_waitcnt vmcnt(7)
	v_fmac_f32_e32 v16, v160, v171
	v_fmac_f32_e32 v17, v161, v171
	v_fmac_f32_e32 v14, v162, v171
	v_fmac_f32_e32 v15, v163, v171
	v_fmac_f32_e32 v12, v160, v187
	v_fmac_f32_e32 v13, v161, v187
	v_fmac_f32_e32 v8, v162, v187
	v_fmac_f32_e32 v9, v163, v187
	v_fmac_f32_e32 v6, v160, v207
	v_fmac_f32_e32 v7, v161, v207
	v_fmac_f32_e32 v2, v162, v207
	v_fmac_f32_e32 v3, v163, v207
	global_load_dwordx4 v[160:163], v[10:11], off nt
	s_waitcnt vmcnt(7)
	v_fmac_f32_e32 v16, v132, v172
	v_fmac_f32_e32 v17, v133, v172
	v_fmac_f32_e32 v14, v134, v172
	v_fmac_f32_e32 v15, v135, v172
	v_fmac_f32_e32 v12, v132, v188
	v_fmac_f32_e32 v13, v133, v188
	v_fmac_f32_e32 v8, v134, v188
	v_fmac_f32_e32 v9, v135, v188
	v_fmac_f32_e32 v6, v132, v208
	v_fmac_f32_e32 v7, v133, v208
	v_fmac_f32_e32 v2, v134, v208
	v_fmac_f32_e32 v3, v135, v208
	s_waitcnt vmcnt(6)
	v_fmac_f32_e32 v16, v136, v173
	v_fmac_f32_e32 v17, v137, v173
	v_fmac_f32_e32 v14, v138, v173
	v_fmac_f32_e32 v15, v139, v173
	v_fmac_f32_e32 v12, v136, v189
	v_fmac_f32_e32 v13, v137, v189
	v_fmac_f32_e32 v8, v138, v189
	v_fmac_f32_e32 v9, v139, v189
	v_fmac_f32_e32 v6, v136, v209
	v_fmac_f32_e32 v7, v137, v209
	v_fmac_f32_e32 v2, v138, v209
	v_fmac_f32_e32 v3, v139, v209
	s_waitcnt vmcnt(5)
	v_fmac_f32_e32 v16, v140, v174
	v_fmac_f32_e32 v17, v141, v174
	v_fmac_f32_e32 v14, v142, v174
	v_fmac_f32_e32 v15, v143, v174
	v_fmac_f32_e32 v12, v140, v190
	v_fmac_f32_e32 v13, v141, v190
	v_fmac_f32_e32 v8, v142, v190
	v_fmac_f32_e32 v9, v143, v190
	v_fmac_f32_e32 v6, v140, v210
	v_fmac_f32_e32 v7, v141, v210
	v_fmac_f32_e32 v2, v142, v210
	v_fmac_f32_e32 v3, v143, v210
	s_waitcnt vmcnt(4)
	v_fmac_f32_e32 v16, v144, v175
	v_fmac_f32_e32 v17, v145, v175
	v_fmac_f32_e32 v14, v146, v175
	v_fmac_f32_e32 v15, v147, v175
	v_fmac_f32_e32 v12, v144, v191
	v_fmac_f32_e32 v13, v145, v191
	v_fmac_f32_e32 v8, v146, v191
	v_fmac_f32_e32 v9, v147, v191
	v_fmac_f32_e32 v6, v144, v211
	v_fmac_f32_e32 v7, v145, v211
	v_fmac_f32_e32 v2, v146, v211
	v_fmac_f32_e32 v3, v147, v211
	s_waitcnt vmcnt(3)
	v_fmac_f32_e32 v16, v148, v176
	v_fmac_f32_e32 v17, v149, v176
	v_fmac_f32_e32 v14, v150, v176
	v_fmac_f32_e32 v15, v151, v176
	v_fmac_f32_e32 v12, v148, v192
	v_fmac_f32_e32 v13, v149, v192
	v_fmac_f32_e32 v8, v150, v192
	v_fmac_f32_e32 v9, v151, v192
	v_fmac_f32_e32 v6, v148, v212
	v_fmac_f32_e32 v7, v149, v212
	v_fmac_f32_e32 v2, v150, v212
	v_fmac_f32_e32 v3, v151, v212
	s_waitcnt vmcnt(2)
	v_fmac_f32_e32 v16, v152, v177
	v_fmac_f32_e32 v17, v153, v177
	v_fmac_f32_e32 v14, v154, v177
	v_fmac_f32_e32 v15, v155, v177
	v_fmac_f32_e32 v12, v152, v193
	v_fmac_f32_e32 v13, v153, v193
	v_fmac_f32_e32 v8, v154, v193
	v_fmac_f32_e32 v9, v155, v193
	v_fmac_f32_e32 v6, v152, v213
	v_fmac_f32_e32 v7, v153, v213
	v_fmac_f32_e32 v2, v154, v213
	v_fmac_f32_e32 v3, v155, v213
	s_waitcnt vmcnt(1)
	v_fmac_f32_e32 v16, v156, v178
	v_fmac_f32_e32 v17, v157, v178
	v_fmac_f32_e32 v14, v158, v178
	v_fmac_f32_e32 v15, v159, v178
	v_fmac_f32_e32 v12, v156, v194
	v_fmac_f32_e32 v13, v157, v194
	v_fmac_f32_e32 v8, v158, v194
	v_fmac_f32_e32 v9, v159, v194
	v_fmac_f32_e32 v6, v156, v214
	v_fmac_f32_e32 v7, v157, v214
	v_fmac_f32_e32 v2, v158, v214
	v_fmac_f32_e32 v3, v159, v214
	s_waitcnt vmcnt(0)
	v_fmac_f32_e32 v16, v160, v179
	v_fmac_f32_e32 v17, v161, v179
	v_fmac_f32_e32 v14, v162, v179
	v_fmac_f32_e32 v15, v163, v179
	v_fmac_f32_e32 v12, v160, v195
	v_fmac_f32_e32 v13, v161, v195
	v_fmac_f32_e32 v8, v162, v195
	v_fmac_f32_e32 v9, v163, v195
	v_fmac_f32_e32 v6, v160, v215
	v_fmac_f32_e32 v7, v161, v215
	v_fmac_f32_e32 v2, v162, v215
	v_fmac_f32_e32 v3, v163, v215
	s_mov_b64 s[4:5], 0x4000
	s_or_b64 exec, exec, s[0:1]

.LBB0_534:
	s_mov_b64 s[0:1], -1
	s_cmpk_gt_i32 s14, 0x2ff
	v_and_b32_e32 v83, 15, v100
	s_cbranch_scc0 .LBB0_538
	v_readlane_b32 s0, v254, 4
	s_add_i32 s3, s14, 0xfffffd00
	s_lshr_b32 s3, s3, 6
	v_mov_b32_e32 v0, s0
	ds_read_b64 v[2:3], v0
	s_lshl_b32 s4, s3, 2
	s_bfe_u32 s2, s14, 0x20004
	s_add_i32 s4, s4, s10
	s_or_b32 s4, s4, s2
	s_ashr_i32 s5, s4, 31
	s_waitcnt lgkmcnt(0)
	v_readfirstlane_b32 s0, v2
	s_lshl_b64 s[4:5], s[4:5], 15
	v_readfirstlane_b32 s1, v3
	s_add_u32 s4, s0, s4
	v_lshlrev_b32_e32 v5, 4, v100
	s_addc_u32 s5, s1, s5
	v_and_b32_e32 v0, 0x70, v5
	v_lshl_add_u64 v[2:3], s[4:5], 0, v[0:1]
	v_add_u32_e32 v10, 0, v0
	v_and_b32_e32 v0, 0x1f0, v5
	v_lshl_add_u64 v[6:7], s[4:5], 0, v[0:1]
	s_mov_b64 s[4:5], 0x9600000
	v_ashrrev_i32_e32 v5, 3, v100
	s_mov_b64 s[8:9], 0x9400000
	v_lshl_add_u64 v[12:13], v[6:7], 0, s[4:5]
	v_lshlrev_b32_e32 v6, 6, v5
	v_lshl_add_u64 v[2:3], v[2:3], 0, s[8:9]
	v_ashrrev_i32_e32 v7, 31, v6
	v_lshl_add_u64 v[6:7], v[6:7], 1, v[2:3]
	global_load_dwordx4 v[132:135], v[6:7], off
	v_mad_u64_u32 v[14:15], s[4:5], v5, s88, v[10:11]
	v_ashrrev_i32_e32 v5, 5, v100
	v_add_u32_e32 v0, 0, v0
	s_movk_i32 s8, 0x210
	s_mov_b64 s[16:17], 0xa000600
	v_mov_b32_e32 v164, v14
	v_lshlrev_b32_e32 v6, 8, v5
	v_ashrrev_i32_e32 v7, 31, v6
	v_lshl_add_u64 v[6:7], v[6:7], 1, v[12:13]
	global_load_dwordx4 v[136:139], v[6:7], off
	v_mad_u64_u32 v[14:15], s[4:5], v5, s8, v[0:1]
	v_add_u32_e32 v5, 0x200, v100
	v_ashrrev_i32_e32 v11, 3, v5
	v_ashrrev_i32_e32 v5, 5, v5
	v_mov_b32_e32 v165, v14
	v_lshlrev_b32_e32 v6, 6, v11
	v_ashrrev_i32_e32 v7, 31, v6
	v_lshl_add_u64 v[6:7], v[6:7], 1, v[2:3]
	global_load_dwordx4 v[140:143], v[6:7], off
	v_mad_u64_u32 v[14:15], s[4:5], v11, s88, v[10:11]
	v_mov_b32_e32 v166, v14
	v_lshlrev_b32_e32 v6, 8, v5
	v_ashrrev_i32_e32 v7, 31, v6
	v_lshl_add_u64 v[6:7], v[6:7], 1, v[12:13]
	global_load_dwordx4 v[144:147], v[6:7], off
	v_mad_u64_u32 v[14:15], s[4:5], v5, s8, v[0:1]
	v_add_u32_e32 v5, 0x400, v100
	v_ashrrev_i32_e32 v11, 3, v5
	v_ashrrev_i32_e32 v5, 5, v5
	v_mov_b32_e32 v167, v14
	v_lshlrev_b32_e32 v6, 6, v11
	v_ashrrev_i32_e32 v7, 31, v6
	v_lshl_add_u64 v[6:7], v[6:7], 1, v[2:3]
	global_load_dwordx4 v[148:151], v[6:7], off
	v_mad_u64_u32 v[14:15], s[4:5], v11, s88, v[10:11]
	v_mov_b32_e32 v168, v14
	v_lshlrev_b32_e32 v6, 8, v5
	v_ashrrev_i32_e32 v7, 31, v6
	v_lshl_add_u64 v[6:7], v[6:7], 1, v[12:13]
	global_load_dwordx4 v[152:155], v[6:7], off
	v_mad_u64_u32 v[14:15], s[4:5], v5, s8, v[0:1]
	v_add_u32_e32 v5, 0x600, v100
	v_ashrrev_i32_e32 v11, 3, v5
	v_ashrrev_i32_e32 v5, 5, v5
	v_mov_b32_e32 v169, v14
	v_lshlrev_b32_e32 v6, 6, v11
	v_ashrrev_i32_e32 v7, 31, v6
	v_lshl_add_u64 v[2:3], v[6:7], 1, v[2:3]
	global_load_dwordx4 v[156:159], v[2:3], off
	v_mad_u64_u32 v[2:3], s[4:5], v11, s88, v[10:11]
	v_mul_u32_u24_e32 v10, 0x90, v83
	v_mov_b32_e32 v170, v2
	v_lshlrev_b32_e32 v2, 8, v5
	v_ashrrev_i32_e32 v3, 31, v2
	v_lshl_add_u64 v[2:3], v[2:3], 1, v[12:13]
	global_load_dwordx4 v[160:163], v[2:3], off
	v_mad_u64_u32 v[2:3], s[4:5], v5, s8, v[0:1]
	s_lshl_b32 s4, s14, 8
	s_and_b32 s4, s4, 0xf00
	s_lshl_b32 s5, s3, 12
	s_add_u32 s3, s0, s13
	s_addc_u32 s8, s1, 0
	s_lshl_b32 s9, s2, 6
	s_lshl_b32 s2, s2, 7
	v_bfe_u32 v5, v100, 4, 2
	v_ashrrev_i32_e32 v0, 2, v100
	s_add_u32 s2, s3, s2
	s_addc_u32 s3, s8, 0
	v_mul_u32_u24_e32 v12, 0x210, v83
	s_lshl_b32 s94, s9, 1
	s_mov_b32 s8, 0xa000000
	v_readlane_b32 s9, v254, 35
	v_mov_b32_e32 v171, v2
	s_waitcnt vmcnt(7)
	ds_write_b128 v164, v[132:135]
	s_waitcnt vmcnt(6)
	ds_write_b128 v165, v[136:139] offset:36864
	s_waitcnt vmcnt(5)
	ds_write_b128 v166, v[140:143]
	s_waitcnt vmcnt(4)
	ds_write_b128 v167, v[144:147] offset:36864
	s_waitcnt vmcnt(3)
	ds_write_b128 v168, v[148:151]
	s_waitcnt vmcnt(2)
	ds_write_b128 v169, v[152:155] offset:36864
	s_waitcnt vmcnt(1)
	ds_write_b128 v170, v[156:159]
	s_waitcnt vmcnt(0)
	ds_write_b128 v171, v[160:163] offset:36864
	v_and_b32_e32 v7, -16, v0
	v_lshlrev_b32_e32 v0, 4, v5
	v_lshl_add_u64 v[2:3], s[2:3], 0, v[0:1]
	s_mov_b64 s[2:3], 0xc400000
	v_lshlrev_b32_e32 v6, 3, v5
	v_lshl_add_u64 v[2:3], v[2:3], 0, s[2:3]
	v_add_u32_e32 v9, 0, v0
	s_or_b32 s2, s5, s4
	v_sub_u32_e32 v11, v9, v6
	v_lshlrev_b32_e32 v8, 2, v5
	v_or_b32_e32 v0, s2, v83
	v_add_u32_e32 v5, v0, v7
	s_mov_b32 s4, 0
	s_mov_b64 s[2:3], -1
	v_lshlrev_b32_e32 v0, 2, v6
	v_add_u32_e32 v30, v9, v10
	v_add_u32_e32 v31, v11, v12
	v_lshlrev_b32_e32 v26, 1, v8
	s_waitcnt lgkmcnt(0)
	s_barrier

.LBB0_569:
	s_or_b64 exec, exec, s[0:1]
	s_mov_b32 s15, s95
	v_and_b32_e32 v7, 15, v2
	s_movk_i32 s2, 0x100
	s_lshl_b64 s[0:1], s[14:15], 18
	v_lshrrev_b32_e32 v13, 4, v3
	v_cmp_gt_i32_e32 vcc, s2, v6
	v_lshlrev_b32_e32 v8, 4, v7
	s_waitcnt lgkmcnt(0)
	s_barrier
	s_and_saveexec_b64 s[2:3], vcc
	s_cbranch_execz .LBB0_574
	v_lshl_add_u32 v15, v7, 4, 0
	v_cmp_eq_u32_e32 vcc, 0, v7
	v_mul_u32_u24_e32 v7, 0x410, v13
	v_lshlrev_b32_e32 v9, 2, v6
	s_add_i32 s6, 0, 0xc00
	v_add3_u32 v14, v7, v9, s6
	v_ashrrev_i32_e32 v7, 31, v6
	v_lshlrev_b64 v[10:11], 10, v[6:7]
	v_and_b32_e32 v7, 48, v2
	v_lshl_add_u64 v[10:11], s[0:1], 0, v[10:11]
	v_lshlrev_b32_e32 v16, 4, v7
	v_mov_b32_e32 v17, v1
	s_add_u32 s6, s34, s12
	v_lshl_add_u64 v[10:11], v[10:11], 0, v[16:17]
	v_mov_b32_e32 v9, v1
	v_lshlrev_b32_e32 v18, 8, v13
	s_addc_u32 s7, s35, s13
	v_lshl_add_u64 v[10:11], v[10:11], 0, v[8:9]
	v_lshl_add_u64 v[10:11], s[6:7], 0, v[10:11]
	s_mov_b64 s[20:21], 0
	v_add_u32_e32 v7, v15, v18
	s_mov_b64 s[6:7], 0x2000
	ds_read_b128 v[20:23], v7
	global_load_dwordx4 v[102:105], v[10:11], off nt
	v_lshl_add_u64 v[10:11], v[10:11], 0, s[6:7]
	global_load_dwordx4 v[106:109], v[10:11], off nt
	v_lshl_add_u64 v[10:11], v[10:11], 0, s[6:7]
	global_load_dwordx4 v[110:113], v[10:11], off nt
	v_lshl_add_u64 v[10:11], v[10:11], 0, s[6:7]
	global_load_dwordx4 v[114:117], v[10:11], off nt
	v_lshl_add_u64 v[10:11], v[10:11], 0, s[6:7]
	global_load_dwordx4 v[118:121], v[10:11], off nt
	v_lshl_add_u64 v[10:11], v[10:11], 0, s[6:7]
	global_load_dwordx4 v[122:125], v[10:11], off nt
	v_lshl_add_u64 v[10:11], v[10:11], 0, s[6:7]
	global_load_dwordx4 v[126:129], v[10:11], off nt
	v_lshl_add_u64 v[10:11], v[10:11], 0, s[6:7]
	global_load_dwordx4 v[130:133], v[10:11], off nt
	v_lshl_add_u64 v[10:11], v[10:11], 0, s[6:7]
	global_load_dwordx4 v[134:137], v[10:11], off nt
	v_lshl_add_u64 v[10:11], v[10:11], 0, s[6:7]
	global_load_dwordx4 v[138:141], v[10:11], off nt
	v_lshl_add_u64 v[10:11], v[10:11], 0, s[6:7]
	global_load_dwordx4 v[142:145], v[10:11], off nt
	v_lshl_add_u64 v[10:11], v[10:11], 0, s[6:7]
	global_load_dwordx4 v[146:149], v[10:11], off nt
	v_lshl_add_u64 v[10:11], v[10:11], 0, s[6:7]
	global_load_dwordx4 v[150:153], v[10:11], off nt
	v_lshl_add_u64 v[10:11], v[10:11], 0, s[6:7]
	global_load_dwordx4 v[154:157], v[10:11], off nt
	v_lshl_add_u64 v[10:11], v[10:11], 0, s[6:7]
	global_load_dwordx4 v[158:161], v[10:11], off nt
	v_lshl_add_u64 v[10:11], v[10:11], 0, s[6:7]
	global_load_dwordx4 v[180:183], v[10:11], off nt
	v_lshl_add_u64 v[10:11], v[10:11], 0, s[6:7]
	s_waitcnt vmcnt(15) lgkmcnt(0)
	v_mul_f32_e32 v200, v103, v21
	v_mul_f32_e32 v216, v105, v23
	v_fmac_f32_e32 v200, v102, v20
	v_fmac_f32_e32 v216, v104, v22
	v_add_f32_e32 v200, v200, v216
	global_load_dwordx4 v[102:105], v[10:11], off nt
	v_lshl_add_u64 v[10:11], v[10:11], 0, s[6:7]
	s_waitcnt vmcnt(15)
	v_mul_f32_e32 v201, v107, v21
	v_mul_f32_e32 v216, v109, v23
	v_fmac_f32_e32 v201, v106, v20
	v_fmac_f32_e32 v216, v108, v22
	v_add_f32_e32 v201, v201, v216
	global_load_dwordx4 v[106:109], v[10:11], off nt
	v_lshl_add_u64 v[10:11], v[10:11], 0, s[6:7]
	s_waitcnt vmcnt(15)
	v_mul_f32_e32 v202, v111, v21
	v_mul_f32_e32 v216, v113, v23
	v_fmac_f32_e32 v202, v110, v20
	v_fmac_f32_e32 v216, v112, v22
	v_add_f32_e32 v202, v202, v216
	global_load_dwordx4 v[110:113], v[10:11], off nt
	v_lshl_add_u64 v[10:11], v[10:11], 0, s[6:7]
	s_waitcnt vmcnt(15)
	v_mul_f32_e32 v203, v115, v21
	v_mul_f32_e32 v216, v117, v23
	v_fmac_f32_e32 v203, v114, v20
	v_fmac_f32_e32 v216, v116, v22
	v_add_f32_e32 v203, v203, v216
	global_load_dwordx4 v[114:117], v[10:11], off nt
	v_lshl_add_u64 v[10:11], v[10:11], 0, s[6:7]
	s_waitcnt vmcnt(15)
	v_mul_f32_e32 v204, v119, v21
	v_mul_f32_e32 v216, v121, v23
	v_fmac_f32_e32 v204, v118, v20
	v_fmac_f32_e32 v216, v120, v22
	v_add_f32_e32 v204, v204, v216
	global_load_dwordx4 v[118:121], v[10:11], off nt
	v_lshl_add_u64 v[10:11], v[10:11], 0, s[6:7]
	s_waitcnt vmcnt(15)
	v_mul_f32_e32 v205, v123, v21
	v_mul_f32_e32 v216, v125, v23
	v_fmac_f32_e32 v205, v122, v20
	v_fmac_f32_e32 v216, v124, v22
	v_add_f32_e32 v205, v205, v216
	global_load_dwordx4 v[122:125], v[10:11], off nt
	v_lshl_add_u64 v[10:11], v[10:11], 0, s[6:7]
	s_waitcnt vmcnt(15)
	v_mul_f32_e32 v206, v127, v21
	v_mul_f32_e32 v216, v129, v23
	v_fmac_f32_e32 v206, v126, v20
	v_fmac_f32_e32 v216, v128, v22
	v_add_f32_e32 v206, v206, v216
	global_load_dwordx4 v[126:129], v[10:11], off nt
	v_lshl_add_u64 v[10:11], v[10:11], 0, s[6:7]
	s_waitcnt vmcnt(15)
	v_mul_f32_e32 v207, v131, v21
	v_mul_f32_e32 v216, v133, v23
	v_fmac_f32_e32 v207, v130, v20
	v_fmac_f32_e32 v216, v132, v22
	v_add_f32_e32 v207, v207, v216
	global_load_dwordx4 v[130:133], v[10:11], off nt
	v_lshl_add_u64 v[10:11], v[10:11], 0, s[6:7]
	s_waitcnt vmcnt(15)
	v_mul_f32_e32 v208, v135, v21
	v_mul_f32_e32 v216, v137, v23
	v_fmac_f32_e32 v208, v134, v20
	v_fmac_f32_e32 v216, v136, v22
	v_add_f32_e32 v208, v208, v216
	global_load_dwordx4 v[134:137], v[10:11], off nt
	v_lshl_add_u64 v[10:11], v[10:11], 0, s[6:7]
	s_waitcnt vmcnt(15)
	v_mul_f32_e32 v209, v139, v21
	v_mul_f32_e32 v216, v141, v23
	v_fmac_f32_e32 v209, v138, v20
	v_fmac_f32_e32 v216, v140, v22
	v_add_f32_e32 v209, v209, v216
	global_load_dwordx4 v[138:141], v[10:11], off nt
	v_lshl_add_u64 v[10:11], v[10:11], 0, s[6:7]
	s_waitcnt vmcnt(15)
	v_mul_f32_e32 v210, v143, v21
	v_mul_f32_e32 v216, v145, v23
	v_fmac_f32_e32 v210, v142, v20
	v_fmac_f32_e32 v216, v144, v22
	v_add_f32_e32 v210, v210, v216
	global_load_dwordx4 v[142:145], v[10:11], off nt
	v_lshl_add_u64 v[10:11], v[10:11], 0, s[6:7]
	s_waitcnt vmcnt(15)
	v_mul_f32_e32 v211, v147, v21
	v_mul_f32_e32 v216, v149, v23
	v_fmac_f32_e32 v211, v146, v20
	v_fmac_f32_e32 v216, v148, v22
	v_add_f32_e32 v211, v211, v216
	global_load_dwordx4 v[146:149], v[10:11], off nt
	v_lshl_add_u64 v[10:11], v[10:11], 0, s[6:7]
	s_waitcnt vmcnt(15)
	v_mul_f32_e32 v212, v151, v21
	v_mul_f32_e32 v216, v153, v23
	v_fmac_f32_e32 v212, v150, v20
	v_fmac_f32_e32 v216, v152, v22
	v_add_f32_e32 v212, v212, v216
	global_load_dwordx4 v[150:153], v[10:11], off nt
	v_lshl_add_u64 v[10:11], v[10:11], 0, s[6:7]
	s_waitcnt vmcnt(15)
	v_mul_f32_e32 v213, v155, v21
	v_mul_f32_e32 v216, v157, v23
	v_fmac_f32_e32 v213, v154, v20
	v_fmac_f32_e32 v216, v156, v22
	v_add_f32_e32 v213, v213, v216
	global_load_dwordx4 v[154:157], v[10:11], off nt
	v_lshl_add_u64 v[10:11], v[10:11], 0, s[6:7]
	s_waitcnt vmcnt(15)
	v_mul_f32_e32 v214, v159, v21
	v_mul_f32_e32 v216, v161, v23
	v_fmac_f32_e32 v214, v158, v20
	v_fmac_f32_e32 v216, v160, v22
	v_add_f32_e32 v214, v214, v216
	global_load_dwordx4 v[158:161], v[10:11], off nt
	v_lshl_add_u64 v[10:11], v[10:11], 0, s[6:7]
	s_waitcnt vmcnt(15)
	v_mul_f32_e32 v215, v181, v21
	v_mul_f32_e32 v216, v183, v23
	v_fmac_f32_e32 v215, v180, v20
	v_fmac_f32_e32 v216, v182, v22
	v_add_f32_e32 v215, v215, v216
	global_load_dwordx4 v[180:183], v[10:11], off nt
	s_waitcnt vmcnt(15)
	v_mul_f32_e32 v232, v103, v21
	v_mul_f32_e32 v216, v105, v23
	v_fmac_f32_e32 v232, v102, v20
	v_fmac_f32_e32 v216, v104, v22
	v_add_f32_e32 v232, v232, v216
	s_waitcnt vmcnt(14)
	v_mul_f32_e32 v233, v107, v21
	v_mul_f32_e32 v216, v109, v23
	v_fmac_f32_e32 v233, v106, v20
	v_fmac_f32_e32 v216, v108, v22
	v_add_f32_e32 v233, v233, v216
	s_waitcnt vmcnt(13)
	v_mul_f32_e32 v234, v111, v21
	v_mul_f32_e32 v216, v113, v23
	v_fmac_f32_e32 v234, v110, v20
	v_fmac_f32_e32 v216, v112, v22
	v_add_f32_e32 v234, v234, v216
	s_waitcnt vmcnt(12)
	v_mul_f32_e32 v235, v115, v21
	v_mul_f32_e32 v216, v117, v23
	v_fmac_f32_e32 v235, v114, v20
	v_fmac_f32_e32 v216, v116, v22
	v_add_f32_e32 v235, v235, v216
	s_waitcnt vmcnt(11)
	v_mul_f32_e32 v236, v119, v21
	v_mul_f32_e32 v216, v121, v23
	v_fmac_f32_e32 v236, v118, v20
	v_fmac_f32_e32 v216, v120, v22
	v_add_f32_e32 v236, v236, v216
	s_waitcnt vmcnt(10)
	v_mul_f32_e32 v237, v123, v21
	v_mul_f32_e32 v216, v125, v23
	v_fmac_f32_e32 v237, v122, v20
	v_fmac_f32_e32 v216, v124, v22
	v_add_f32_e32 v237, v237, v216
	s_waitcnt vmcnt(9)
	v_mul_f32_e32 v238, v127, v21
	v_mul_f32_e32 v216, v129, v23
	v_fmac_f32_e32 v238, v126, v20
	v_fmac_f32_e32 v216, v128, v22
	v_add_f32_e32 v238, v238, v216
	s_waitcnt vmcnt(8)
	v_mul_f32_e32 v239, v131, v21
	v_mul_f32_e32 v216, v133, v23
	v_fmac_f32_e32 v239, v130, v20
	v_fmac_f32_e32 v216, v132, v22
	v_add_f32_e32 v239, v239, v216
	s_waitcnt vmcnt(7)
	v_mul_f32_e32 v240, v135, v21
	v_mul_f32_e32 v216, v137, v23
	v_fmac_f32_e32 v240, v134, v20
	v_fmac_f32_e32 v216, v136, v22
	v_add_f32_e32 v240, v240, v216
	s_waitcnt vmcnt(6)
	v_mul_f32_e32 v241, v139, v21
	v_mul_f32_e32 v216, v141, v23
	v_fmac_f32_e32 v241, v138, v20
	v_fmac_f32_e32 v216, v140, v22
	v_add_f32_e32 v241, v241, v216
	s_waitcnt vmcnt(5)
	v_mul_f32_e32 v242, v143, v21
	v_mul_f32_e32 v216, v145, v23
	v_fmac_f32_e32 v242, v142, v20
	v_fmac_f32_e32 v216, v144, v22
	v_add_f32_e32 v242, v242, v216
	s_waitcnt vmcnt(4)
	v_mul_f32_e32 v243, v147, v21
	v_mul_f32_e32 v216, v149, v23
	v_fmac_f32_e32 v243, v146, v20
	v_fmac_f32_e32 v216, v148, v22
	v_add_f32_e32 v243, v243, v216
	s_waitcnt vmcnt(3)
	v_mul_f32_e32 v244, v151, v21
	v_mul_f32_e32 v216, v153, v23
	v_fmac_f32_e32 v244, v150, v20
	v_fmac_f32_e32 v216, v152, v22
	v_add_f32_e32 v244, v244, v216
	s_waitcnt vmcnt(2)
	v_mul_f32_e32 v245, v155, v21
	v_mul_f32_e32 v216, v157, v23
	v_fmac_f32_e32 v245, v154, v20
	v_fmac_f32_e32 v216, v156, v22
	v_add_f32_e32 v245, v245, v216
	s_waitcnt vmcnt(1)
	v_mul_f32_e32 v246, v159, v21
	v_mul_f32_e32 v216, v161, v23
	v_fmac_f32_e32 v246, v158, v20
	v_fmac_f32_e32 v216, v160, v22
	v_add_f32_e32 v246, v246, v216
	s_waitcnt vmcnt(0)
	v_mul_f32_e32 v247, v181, v21
	v_mul_f32_e32 v216, v183, v23
	v_fmac_f32_e32 v247, v180, v20
	v_fmac_f32_e32 v216, v182, v22
	v_add_f32_e32 v247, v247, v216
	s_nop 1
	v_add_f32_dpp v200, v200, v200 quad_perm:[1,0,3,2] row_mask:0xf bank_mask:0xf
	v_add_f32_dpp v201, v201, v201 quad_perm:[1,0,3,2] row_mask:0xf bank_mask:0xf
	v_add_f32_dpp v202, v202, v202 quad_perm:[1,0,3,2] row_mask:0xf bank_mask:0xf
	v_add_f32_dpp v203, v203, v203 quad_perm:[1,0,3,2] row_mask:0xf bank_mask:0xf
	v_add_f32_dpp v204, v204, v204 quad_perm:[1,0,3,2] row_mask:0xf bank_mask:0xf
	v_add_f32_dpp v205, v205, v205 quad_perm:[1,0,3,2] row_mask:0xf bank_mask:0xf
	v_add_f32_dpp v206, v206, v206 quad_perm:[1,0,3,2] row_mask:0xf bank_mask:0xf
	v_add_f32_dpp v207, v207, v207 quad_perm:[1,0,3,2] row_mask:0xf bank_mask:0xf
	v_add_f32_dpp v208, v208, v208 quad_perm:[1,0,3,2] row_mask:0xf bank_mask:0xf
	v_add_f32_dpp v209, v209, v209 quad_perm:[1,0,3,2] row_mask:0xf bank_mask:0xf
	v_add_f32_dpp v210, v210, v210 quad_perm:[1,0,3,2] row_mask:0xf bank_mask:0xf
	v_add_f32_dpp v211, v211, v211 quad_perm:[1,0,3,2] row_mask:0xf bank_mask:0xf
	v_add_f32_dpp v212, v212, v212 quad_perm:[1,0,3,2] row_mask:0xf bank_mask:0xf
	v_add_f32_dpp v213, v213, v213 quad_perm:[1,0,3,2] row_mask:0xf bank_mask:0xf
	v_add_f32_dpp v214, v214, v214 quad_perm:[1,0,3,2] row_mask:0xf bank_mask:0xf
	v_add_f32_dpp v215, v215, v215 quad_perm:[1,0,3,2] row_mask:0xf bank_mask:0xf
	v_add_f32_dpp v232, v232, v232 quad_perm:[1,0,3,2] row_mask:0xf bank_mask:0xf
	v_add_f32_dpp v233, v233, v233 quad_perm:[1,0,3,2] row_mask:0xf bank_mask:0xf
	v_add_f32_dpp v234, v234, v234 quad_perm:[1,0,3,2] row_mask:0xf bank_mask:0xf
	v_add_f32_dpp v235, v235, v235 quad_perm:[1,0,3,2] row_mask:0xf bank_mask:0xf
	v_add_f32_dpp v236, v236, v236 quad_perm:[1,0,3,2] row_mask:0xf bank_mask:0xf
	v_add_f32_dpp v237, v237, v237 quad_perm:[1,0,3,2] row_mask:0xf bank_mask:0xf
	v_add_f32_dpp v238, v238, v238 quad_perm:[1,0,3,2] row_mask:0xf bank_mask:0xf
	v_add_f32_dpp v239, v239, v239 quad_perm:[1,0,3,2] row_mask:0xf bank_mask:0xf
	v_add_f32_dpp v240, v240, v240 quad_perm:[1,0,3,2] row_mask:0xf bank_mask:0xf
	v_add_f32_dpp v241, v241, v241 quad_perm:[1,0,3,2] row_mask:0xf bank_mask:0xf
	v_add_f32_dpp v242, v242, v242 quad_perm:[1,0,3,2] row_mask:0xf bank_mask:0xf
	v_add_f32_dpp v243, v243, v243 quad_perm:[1,0,3,2] row_mask:0xf bank_mask:0xf
	v_add_f32_dpp v244, v244, v244 quad_perm:[1,0,3,2] row_mask:0xf bank_mask:0xf
	v_add_f32_dpp v245, v245, v245 quad_perm:[1,0,3,2] row_mask:0xf bank_mask:0xf
	v_add_f32_dpp v246, v246, v246 quad_perm:[1,0,3,2] row_mask:0xf bank_mask:0xf
	v_add_f32_dpp v247, v247, v247 quad_perm:[1,0,3,2] row_mask:0xf bank_mask:0xf
	v_add_f32_dpp v200, v200, v200 quad_perm:[2,3,0,1] row_mask:0xf bank_mask:0xf
	v_add_f32_dpp v201, v201, v201 quad_perm:[2,3,0,1] row_mask:0xf bank_mask:0xf
	v_add_f32_dpp v202, v202, v202 quad_perm:[2,3,0,1] row_mask:0xf bank_mask:0xf
	v_add_f32_dpp v203, v203, v203 quad_perm:[2,3,0,1] row_mask:0xf bank_mask:0xf
	v_add_f32_dpp v204, v204, v204 quad_perm:[2,3,0,1] row_mask:0xf bank_mask:0xf
	v_add_f32_dpp v205, v205, v205 quad_perm:[2,3,0,1] row_mask:0xf bank_mask:0xf
	v_add_f32_dpp v206, v206, v206 quad_perm:[2,3,0,1] row_mask:0xf bank_mask:0xf
	v_add_f32_dpp v207, v207, v207 quad_perm:[2,3,0,1] row_mask:0xf bank_mask:0xf
	v_add_f32_dpp v208, v208, v208 quad_perm:[2,3,0,1] row_mask:0xf bank_mask:0xf
	v_add_f32_dpp v209, v209, v209 quad_perm:[2,3,0,1] row_mask:0xf bank_mask:0xf
	v_add_f32_dpp v210, v210, v210 quad_perm:[2,3,0,1] row_mask:0xf bank_mask:0xf
	v_add_f32_dpp v211, v211, v211 quad_perm:[2,3,0,1] row_mask:0xf bank_mask:0xf
	v_add_f32_dpp v212, v212, v212 quad_perm:[2,3,0,1] row_mask:0xf bank_mask:0xf
	v_add_f32_dpp v213, v213, v213 quad_perm:[2,3,0,1] row_mask:0xf bank_mask:0xf
	v_add_f32_dpp v214, v214, v214 quad_perm:[2,3,0,1] row_mask:0xf bank_mask:0xf
	v_add_f32_dpp v215, v215, v215 quad_perm:[2,3,0,1] row_mask:0xf bank_mask:0xf
	v_add_f32_dpp v232, v232, v232 quad_perm:[2,3,0,1] row_mask:0xf bank_mask:0xf
	v_add_f32_dpp v233, v233, v233 quad_perm:[2,3,0,1] row_mask:0xf bank_mask:0xf
	v_add_f32_dpp v234, v234, v234 quad_perm:[2,3,0,1] row_mask:0xf bank_mask:0xf
	v_add_f32_dpp v235, v235, v235 quad_perm:[2,3,0,1] row_mask:0xf bank_mask:0xf
	v_add_f32_dpp v236, v236, v236 quad_perm:[2,3,0,1] row_mask:0xf bank_mask:0xf
	v_add_f32_dpp v237, v237, v237 quad_perm:[2,3,0,1] row_mask:0xf bank_mask:0xf
	v_add_f32_dpp v238, v238, v238 quad_perm:[2,3,0,1] row_mask:0xf bank_mask:0xf
	v_add_f32_dpp v239, v239, v239 quad_perm:[2,3,0,1] row_mask:0xf bank_mask:0xf
	v_add_f32_dpp v240, v240, v240 quad_perm:[2,3,0,1] row_mask:0xf bank_mask:0xf
	v_add_f32_dpp v241, v241, v241 quad_perm:[2,3,0,1] row_mask:0xf bank_mask:0xf
	v_add_f32_dpp v242, v242, v242 quad_perm:[2,3,0,1] row_mask:0xf bank_mask:0xf
	v_add_f32_dpp v243, v243, v243 quad_perm:[2,3,0,1] row_mask:0xf bank_mask:0xf
	v_add_f32_dpp v244, v244, v244 quad_perm:[2,3,0,1] row_mask:0xf bank_mask:0xf
	v_add_f32_dpp v245, v245, v245 quad_perm:[2,3,0,1] row_mask:0xf bank_mask:0xf
	v_add_f32_dpp v246, v246, v246 quad_perm:[2,3,0,1] row_mask:0xf bank_mask:0xf
	v_add_f32_dpp v247, v247, v247 quad_perm:[2,3,0,1] row_mask:0xf bank_mask:0xf
	v_add_f32_dpp v200, v200, v200 row_ror:4 row_mask:0xf bank_mask:0xf
	v_add_f32_dpp v201, v201, v201 row_ror:4 row_mask:0xf bank_mask:0xf
	v_add_f32_dpp v202, v202, v202 row_ror:4 row_mask:0xf bank_mask:0xf
	v_add_f32_dpp v203, v203, v203 row_ror:4 row_mask:0xf bank_mask:0xf
	v_add_f32_dpp v204, v204, v204 row_ror:4 row_mask:0xf bank_mask:0xf
	v_add_f32_dpp v205, v205, v205 row_ror:4 row_mask:0xf bank_mask:0xf
	v_add_f32_dpp v206, v206, v206 row_ror:4 row_mask:0xf bank_mask:0xf
	v_add_f32_dpp v207, v207, v207 row_ror:4 row_mask:0xf bank_mask:0xf
	v_add_f32_dpp v208, v208, v208 row_ror:4 row_mask:0xf bank_mask:0xf
	v_add_f32_dpp v209, v209, v209 row_ror:4 row_mask:0xf bank_mask:0xf
	v_add_f32_dpp v210, v210, v210 row_ror:4 row_mask:0xf bank_mask:0xf
	v_add_f32_dpp v211, v211, v211 row_ror:4 row_mask:0xf bank_mask:0xf
	v_add_f32_dpp v212, v212, v212 row_ror:4 row_mask:0xf bank_mask:0xf
	v_add_f32_dpp v213, v213, v213 row_ror:4 row_mask:0xf bank_mask:0xf
	v_add_f32_dpp v214, v214, v214 row_ror:4 row_mask:0xf bank_mask:0xf
	v_add_f32_dpp v215, v215, v215 row_ror:4 row_mask:0xf bank_mask:0xf
	v_add_f32_dpp v232, v232, v232 row_ror:4 row_mask:0xf bank_mask:0xf
	v_add_f32_dpp v233, v233, v233 row_ror:4 row_mask:0xf bank_mask:0xf
	v_add_f32_dpp v234, v234, v234 row_ror:4 row_mask:0xf bank_mask:0xf
	v_add_f32_dpp v235, v235, v235 row_ror:4 row_mask:0xf bank_mask:0xf
	v_add_f32_dpp v236, v236, v236 row_ror:4 row_mask:0xf bank_mask:0xf
	v_add_f32_dpp v237, v237, v237 row_ror:4 row_mask:0xf bank_mask:0xf
	v_add_f32_dpp v238, v238, v238 row_ror:4 row_mask:0xf bank_mask:0xf
	v_add_f32_dpp v239, v239, v239 row_ror:4 row_mask:0xf bank_mask:0xf
	v_add_f32_dpp v240, v240, v240 row_ror:4 row_mask:0xf bank_mask:0xf
	v_add_f32_dpp v241, v241, v241 row_ror:4 row_mask:0xf bank_mask:0xf
	v_add_f32_dpp v242, v242, v242 row_ror:4 row_mask:0xf bank_mask:0xf
	v_add_f32_dpp v243, v243, v243 row_ror:4 row_mask:0xf bank_mask:0xf
	v_add_f32_dpp v244, v244, v244 row_ror:4 row_mask:0xf bank_mask:0xf
	v_add_f32_dpp v245, v245, v245 row_ror:4 row_mask:0xf bank_mask:0xf
	v_add_f32_dpp v246, v246, v246 row_ror:4 row_mask:0xf bank_mask:0xf
	v_add_f32_dpp v247, v247, v247 row_ror:4 row_mask:0xf bank_mask:0xf
	v_add_f32_dpp v200, v200, v200 row_ror:8 row_mask:0xf bank_mask:0xf
	v_add_f32_dpp v201, v201, v201 row_ror:8 row_mask:0xf bank_mask:0xf
	v_add_f32_dpp v202, v202, v202 row_ror:8 row_mask:0xf bank_mask:0xf
	v_add_f32_dpp v203, v203, v203 row_ror:8 row_mask:0xf bank_mask:0xf
	v_add_f32_dpp v204, v204, v204 row_ror:8 row_mask:0xf bank_mask:0xf
	v_add_f32_dpp v205, v205, v205 row_ror:8 row_mask:0xf bank_mask:0xf
	v_add_f32_dpp v206, v206, v206 row_ror:8 row_mask:0xf bank_mask:0xf
	v_add_f32_dpp v207, v207, v207 row_ror:8 row_mask:0xf bank_mask:0xf
	v_add_f32_dpp v208, v208, v208 row_ror:8 row_mask:0xf bank_mask:0xf
	v_add_f32_dpp v209, v209, v209 row_ror:8 row_mask:0xf bank_mask:0xf
	v_add_f32_dpp v210, v210, v210 row_ror:8 row_mask:0xf bank_mask:0xf
	v_add_f32_dpp v211, v211, v211 row_ror:8 row_mask:0xf bank_mask:0xf
	v_add_f32_dpp v212, v212, v212 row_ror:8 row_mask:0xf bank_mask:0xf
	v_add_f32_dpp v213, v213, v213 row_ror:8 row_mask:0xf bank_mask:0xf
	v_add_f32_dpp v214, v214, v214 row_ror:8 row_mask:0xf bank_mask:0xf
	v_add_f32_dpp v215, v215, v215 row_ror:8 row_mask:0xf bank_mask:0xf
	v_add_f32_dpp v232, v232, v232 row_ror:8 row_mask:0xf bank_mask:0xf
	v_add_f32_dpp v233, v233, v233 row_ror:8 row_mask:0xf bank_mask:0xf
	v_add_f32_dpp v234, v234, v234 row_ror:8 row_mask:0xf bank_mask:0xf
	v_add_f32_dpp v235, v235, v235 row_ror:8 row_mask:0xf bank_mask:0xf
	v_add_f32_dpp v236, v236, v236 row_ror:8 row_mask:0xf bank_mask:0xf
	v_add_f32_dpp v237, v237, v237 row_ror:8 row_mask:0xf bank_mask:0xf
	v_add_f32_dpp v238, v238, v238 row_ror:8 row_mask:0xf bank_mask:0xf
	v_add_f32_dpp v239, v239, v239 row_ror:8 row_mask:0xf bank_mask:0xf
	v_add_f32_dpp v240, v240, v240 row_ror:8 row_mask:0xf bank_mask:0xf
	v_add_f32_dpp v241, v241, v241 row_ror:8 row_mask:0xf bank_mask:0xf
	v_add_f32_dpp v242, v242, v242 row_ror:8 row_mask:0xf bank_mask:0xf
	v_add_f32_dpp v243, v243, v243 row_ror:8 row_mask:0xf bank_mask:0xf
	v_add_f32_dpp v244, v244, v244 row_ror:8 row_mask:0xf bank_mask:0xf
	v_add_f32_dpp v245, v245, v245 row_ror:8 row_mask:0xf bank_mask:0xf
	v_add_f32_dpp v246, v246, v246 row_ror:8 row_mask:0xf bank_mask:0xf
	v_add_f32_dpp v247, v247, v247 row_ror:8 row_mask:0xf bank_mask:0xf
	s_and_saveexec_b64 s[20:21], vcc
	s_nop 0
	ds_write_b32 v14, v200 offset:0
	ds_write_b32 v14, v201 offset:32
	ds_write_b32 v14, v202 offset:64
	ds_write_b32 v14, v203 offset:96
	ds_write_b32 v14, v204 offset:128
	ds_write_b32 v14, v205 offset:160
	ds_write_b32 v14, v206 offset:192
	ds_write_b32 v14, v207 offset:224
	ds_write_b32 v14, v208 offset:256
	ds_write_b32 v14, v209 offset:288
	ds_write_b32 v14, v210 offset:320
	ds_write_b32 v14, v211 offset:352
	ds_write_b32 v14, v212 offset:384
	ds_write_b32 v14, v213 offset:416
	ds_write_b32 v14, v214 offset:448
	ds_write_b32 v14, v215 offset:480
	ds_write_b32 v14, v232 offset:512
	ds_write_b32 v14, v233 offset:544
	ds_write_b32 v14, v234 offset:576
	ds_write_b32 v14, v235 offset:608
	ds_write_b32 v14, v236 offset:640
	ds_write_b32 v14, v237 offset:672
	ds_write_b32 v14, v238 offset:704
	ds_write_b32 v14, v239 offset:736
	ds_write_b32 v14, v240 offset:768
	ds_write_b32 v14, v241 offset:800
	ds_write_b32 v14, v242 offset:832
	ds_write_b32 v14, v243 offset:864
	ds_write_b32 v14, v244 offset:896
	ds_write_b32 v14, v245 offset:928
	ds_write_b32 v14, v246 offset:960
	ds_write_b32 v14, v247 offset:992
	s_or_b64 exec, exec, s[20:21]

.LBB0_587:
	s_or_b64 exec, exec, s[2:3]
	v_cmp_lt_u32_e32 vcc, 11, v15
	s_and_saveexec_b64 s[2:3], vcc
	s_cbranch_execz .LBB0_591
	s_lshl_b64 s[4:5], s[94:95], 16
	s_add_u32 s4, s4, s8
	s_addc_u32 s5, s5, s9
	s_lshl_b64 s[4:5], s[4:5], 2
	s_add_u32 s4, s17, s4
	s_addc_u32 s5, s31, s5
	v_lshlrev_b32_e32 v12, 8, v19
	v_mov_b32_e32 v13, v1
	v_lshl_add_u64 v[12:13], s[4:5], 0, v[12:13]
	v_lshlrev_b32_e32 v15, 2, v16
	s_add_i32 s4, 0, 0xc00
	v_add3_u32 v21, v14, v15, s4
	v_add_u32_e32 v14, 12, v16
	v_ashrrev_i32_e32 v15, 31, v14
	v_ashrrev_i32_e32 v17, 31, v16
	v_add_u32_e32 v22, -4, v16
	v_lshlrev_b64 v[14:15], 10, v[14:15]
	v_lshlrev_b64 v[16:17], 10, v[16:17]
	v_lshl_add_u64 v[14:15], s[0:1], 0, v[14:15]
	v_lshl_add_u64 v[16:17], s[0:1], 0, v[16:17]
	v_mov_b32_e32 v9, v1
	s_add_u32 s4, s17, s12
	v_lshl_add_u64 v[14:15], v[14:15], 0, v[0:1]
	v_lshl_add_u64 v[16:17], v[16:17], 0, v[0:1]
	s_addc_u32 s5, s31, s13
	v_lshl_add_u64 v[14:15], v[14:15], 0, v[8:9]
	v_lshl_add_u64 v[16:17], v[16:17], 0, v[8:9]
	v_lshl_add_u64 v[12:13], v[12:13], 0, v[8:9]
	v_lshl_add_u64 v[14:15], s[4:5], 0, v[14:15]
	v_lshl_add_u64 v[16:17], s[4:5], 0, v[16:17]
	s_mov_b64 s[0:1], 0
	s_mov_b64 s[4:5], 0x4000
	s_mov_b64 s[4:5], 0x1000
	ds_read2_b32 v[200:201], v21 offset0:0 offset1:4
	ds_read2_b32 v[202:203], v21 offset0:8 offset1:12
	ds_read2_b32 v[204:205], v21 offset0:16 offset1:20
	ds_read2_b32 v[206:207], v21 offset0:24 offset1:28
	ds_read2_b32 v[208:209], v21 offset0:32 offset1:36
	ds_read2_b32 v[210:211], v21 offset0:40 offset1:44
	ds_read2_b32 v[212:213], v21 offset0:48 offset1:52
	ds_read2_b32 v[214:215], v21 offset0:56 offset1:60
	ds_read2_b32 v[232:233], v21 offset0:64 offset1:68
	ds_read2_b32 v[234:235], v21 offset0:72 offset1:76
	ds_read2_b32 v[236:237], v21 offset0:80 offset1:84
	ds_read2_b32 v[238:239], v21 offset0:88 offset1:92
	ds_read2_b32 v[240:241], v21 offset0:96 offset1:100
	ds_read2_b32 v[242:243], v21 offset0:104 offset1:108
	ds_read2_b32 v[244:245], v21 offset0:112 offset1:116
	ds_read2_b32 v[246:247], v21 offset0:120 offset1:124
	global_load_dwordx4 v[102:105], v[16:17], off nt
	v_lshl_add_u64 v[16:17], v[16:17], 0, s[4:5]
	global_load_dwordx4 v[106:109], v[16:17], off nt
	v_lshl_add_u64 v[16:17], v[16:17], 0, s[4:5]
	global_load_dwordx4 v[110:113], v[16:17], off nt
	v_lshl_add_u64 v[16:17], v[16:17], 0, s[4:5]
	global_load_dwordx4 v[114:117], v[16:17], off nt
	v_lshl_add_u64 v[16:17], v[16:17], 0, s[4:5]
	global_load_dwordx4 v[118:121], v[16:17], off nt
	v_lshl_add_u64 v[16:17], v[16:17], 0, s[4:5]
	global_load_dwordx4 v[122:125], v[16:17], off nt
	v_lshl_add_u64 v[16:17], v[16:17], 0, s[4:5]
	global_load_dwordx4 v[126:129], v[16:17], off nt
	v_lshl_add_u64 v[16:17], v[16:17], 0, s[4:5]
	global_load_dwordx4 v[130:133], v[16:17], off nt
	v_lshl_add_u64 v[16:17], v[16:17], 0, s[4:5]
	global_load_dwordx4 v[134:137], v[16:17], off nt
	v_lshl_add_u64 v[16:17], v[16:17], 0, s[4:5]
	global_load_dwordx4 v[138:141], v[16:17], off nt
	v_lshl_add_u64 v[16:17], v[16:17], 0, s[4:5]
	global_load_dwordx4 v[142:145], v[16:17], off nt
	v_lshl_add_u64 v[16:17], v[16:17], 0, s[4:5]
	global_load_dwordx4 v[146:149], v[16:17], off nt
	v_lshl_add_u64 v[16:17], v[16:17], 0, s[4:5]
	global_load_dwordx4 v[150:153], v[16:17], off nt
	v_lshl_add_u64 v[16:17], v[16:17], 0, s[4:5]
	global_load_dwordx4 v[154:157], v[16:17], off nt
	v_lshl_add_u64 v[16:17], v[16:17], 0, s[4:5]
	global_load_dwordx4 v[158:161], v[16:17], off nt
	v_lshl_add_u64 v[16:17], v[16:17], 0, s[4:5]
	global_load_dwordx4 v[180:183], v[16:17], off nt
	v_lshl_add_u64 v[16:17], v[16:17], 0, s[4:5]
	s_waitcnt vmcnt(15) lgkmcnt(0)
	v_fmac_f32_e32 v10, v102, v200
	v_fmac_f32_e32 v11, v103, v200
	v_fmac_f32_e32 v6, v104, v200
	v_fmac_f32_e32 v7, v105, v200
	global_load_dwordx4 v[102:105], v[16:17], off nt
	v_lshl_add_u64 v[16:17], v[16:17], 0, s[4:5]
	s_waitcnt vmcnt(15)
	v_fmac_f32_e32 v10, v106, v201
	v_fmac_f32_e32 v11, v107, v201
	v_fmac_f32_e32 v6, v108, v201
	v_fmac_f32_e32 v7, v109, v201
	global_load_dwordx4 v[106:109], v[16:17], off nt
	v_lshl_add_u64 v[16:17], v[16:17], 0, s[4:5]
	s_waitcnt vmcnt(15)
	v_fmac_f32_e32 v10, v110, v202
	v_fmac_f32_e32 v11, v111, v202
	v_fmac_f32_e32 v6, v112, v202
	v_fmac_f32_e32 v7, v113, v202
	global_load_dwordx4 v[110:113], v[16:17], off nt
	v_lshl_add_u64 v[16:17], v[16:17], 0, s[4:5]
	s_waitcnt vmcnt(15)
	v_fmac_f32_e32 v10, v114, v203
	v_fmac_f32_e32 v11, v115, v203
	v_fmac_f32_e32 v6, v116, v203
	v_fmac_f32_e32 v7, v117, v203
	global_load_dwordx4 v[114:117], v[16:17], off nt
	v_lshl_add_u64 v[16:17], v[16:17], 0, s[4:5]
	s_waitcnt vmcnt(15)
	v_fmac_f32_e32 v10, v118, v204
	v_fmac_f32_e32 v11, v119, v204
	v_fmac_f32_e32 v6, v120, v204
	v_fmac_f32_e32 v7, v121, v204
	global_load_dwordx4 v[118:121], v[16:17], off nt
	v_lshl_add_u64 v[16:17], v[16:17], 0, s[4:5]
	s_waitcnt vmcnt(15)
	v_fmac_f32_e32 v10, v122, v205
	v_fmac_f32_e32 v11, v123, v205
	v_fmac_f32_e32 v6, v124, v205
	v_fmac_f32_e32 v7, v125, v205
	global_load_dwordx4 v[122:125], v[16:17], off nt
	v_lshl_add_u64 v[16:17], v[16:17], 0, s[4:5]
	s_waitcnt vmcnt(15)
	v_fmac_f32_e32 v10, v126, v206
	v_fmac_f32_e32 v11, v127, v206
	v_fmac_f32_e32 v6, v128, v206
	v_fmac_f32_e32 v7, v129, v206
	global_load_dwordx4 v[126:129], v[16:17], off nt
	v_lshl_add_u64 v[16:17], v[16:17], 0, s[4:5]
	s_waitcnt vmcnt(15)
	v_fmac_f32_e32 v10, v130, v207
	v_fmac_f32_e32 v11, v131, v207
	v_fmac_f32_e32 v6, v132, v207
	v_fmac_f32_e32 v7, v133, v207
	global_load_dwordx4 v[130:133], v[16:17], off nt
	v_lshl_add_u64 v[16:17], v[16:17], 0, s[4:5]
	s_waitcnt vmcnt(15)
	v_fmac_f32_e32 v10, v134, v208
	v_fmac_f32_e32 v11, v135, v208
	v_fmac_f32_e32 v6, v136, v208
	v_fmac_f32_e32 v7, v137, v208
	global_load_dwordx4 v[134:137], v[16:17], off nt
	v_lshl_add_u64 v[16:17], v[16:17], 0, s[4:5]
	s_waitcnt vmcnt(15)
	v_fmac_f32_e32 v10, v138, v209
	v_fmac_f32_e32 v11, v139, v209
	v_fmac_f32_e32 v6, v140, v209
	v_fmac_f32_e32 v7, v141, v209
	global_load_dwordx4 v[138:141], v[16:17], off nt
	v_lshl_add_u64 v[16:17], v[16:17], 0, s[4:5]
	s_waitcnt vmcnt(15)
	v_fmac_f32_e32 v10, v142, v210
	v_fmac_f32_e32 v11, v143, v210
	v_fmac_f32_e32 v6, v144, v210
	v_fmac_f32_e32 v7, v145, v210
	global_load_dwordx4 v[142:145], v[16:17], off nt
	v_lshl_add_u64 v[16:17], v[16:17], 0, s[4:5]
	s_waitcnt vmcnt(15)
	v_fmac_f32_e32 v10, v146, v211
	v_fmac_f32_e32 v11, v147, v211
	v_fmac_f32_e32 v6, v148, v211
	v_fmac_f32_e32 v7, v149, v211
	global_load_dwordx4 v[146:149], v[16:17], off nt
	v_lshl_add_u64 v[16:17], v[16:17], 0, s[4:5]
	s_waitcnt vmcnt(15)
	v_fmac_f32_e32 v10, v150, v212
	v_fmac_f32_e32 v11, v151, v212
	v_fmac_f32_e32 v6, v152, v212
	v_fmac_f32_e32 v7, v153, v212
	global_load_dwordx4 v[150:153], v[16:17], off nt
	v_lshl_add_u64 v[16:17], v[16:17], 0, s[4:5]
	s_waitcnt vmcnt(15)
	v_fmac_f32_e32 v10, v154, v213
	v_fmac_f32_e32 v11, v155, v213
	v_fmac_f32_e32 v6, v156, v213
	v_fmac_f32_e32 v7, v157, v213
	global_load_dwordx4 v[154:157], v[16:17], off nt
	v_lshl_add_u64 v[16:17], v[16:17], 0, s[4:5]
	s_waitcnt vmcnt(15)
	v_fmac_f32_e32 v10, v158, v214
	v_fmac_f32_e32 v11, v159, v214
	v_fmac_f32_e32 v6, v160, v214
	v_fmac_f32_e32 v7, v161, v214
	global_load_dwordx4 v[158:161], v[16:17], off nt
	v_lshl_add_u64 v[16:17], v[16:17], 0, s[4:5]
	s_waitcnt vmcnt(15)
	v_fmac_f32_e32 v10, v180, v215
	v_fmac_f32_e32 v11, v181, v215
	v_fmac_f32_e32 v6, v182, v215
	v_fmac_f32_e32 v7, v183, v215
	global_load_dwordx4 v[180:183], v[16:17], off nt
	s_waitcnt vmcnt(15)
	v_fmac_f32_e32 v10, v102, v232
	v_fmac_f32_e32 v11, v103, v232
	v_fmac_f32_e32 v6, v104, v232
	v_fmac_f32_e32 v7, v105, v232
	s_waitcnt vmcnt(14)
	v_fmac_f32_e32 v10, v106, v233
	v_fmac_f32_e32 v11, v107, v233
	v_fmac_f32_e32 v6, v108, v233
	v_fmac_f32_e32 v7, v109, v233
	s_waitcnt vmcnt(13)
	v_fmac_f32_e32 v10, v110, v234
	v_fmac_f32_e32 v11, v111, v234
	v_fmac_f32_e32 v6, v112, v234
	v_fmac_f32_e32 v7, v113, v234
	s_waitcnt vmcnt(12)
	v_fmac_f32_e32 v10, v114, v235
	v_fmac_f32_e32 v11, v115, v235
	v_fmac_f32_e32 v6, v116, v235
	v_fmac_f32_e32 v7, v117, v235
	s_waitcnt vmcnt(11)
	v_fmac_f32_e32 v10, v118, v236
	v_fmac_f32_e32 v11, v119, v236
	v_fmac_f32_e32 v6, v120, v236
	v_fmac_f32_e32 v7, v121, v236
	s_waitcnt vmcnt(10)
	v_fmac_f32_e32 v10, v122, v237
	v_fmac_f32_e32 v11, v123, v237
	v_fmac_f32_e32 v6, v124, v237
	v_fmac_f32_e32 v7, v125, v237
	s_waitcnt vmcnt(9)
	v_fmac_f32_e32 v10, v126, v238
	v_fmac_f32_e32 v11, v127, v238
	v_fmac_f32_e32 v6, v128, v238
	v_fmac_f32_e32 v7, v129, v238
	s_waitcnt vmcnt(8)
	v_fmac_f32_e32 v10, v130, v239
	v_fmac_f32_e32 v11, v131, v239
	v_fmac_f32_e32 v6, v132, v239
	v_fmac_f32_e32 v7, v133, v239
	s_waitcnt vmcnt(7)
	v_fmac_f32_e32 v10, v134, v240
	v_fmac_f32_e32 v11, v135, v240
	v_fmac_f32_e32 v6, v136, v240
	v_fmac_f32_e32 v7, v137, v240
	s_waitcnt vmcnt(6)
	v_fmac_f32_e32 v10, v138, v241
	v_fmac_f32_e32 v11, v139, v241
	v_fmac_f32_e32 v6, v140, v241
	v_fmac_f32_e32 v7, v141, v241
	s_waitcnt vmcnt(5)
	v_fmac_f32_e32 v10, v142, v242
	v_fmac_f32_e32 v11, v143, v242
	v_fmac_f32_e32 v6, v144, v242
	v_fmac_f32_e32 v7, v145, v242
	s_waitcnt vmcnt(4)
	v_fmac_f32_e32 v10, v146, v243
	v_fmac_f32_e32 v11, v147, v243
	v_fmac_f32_e32 v6, v148, v243
	v_fmac_f32_e32 v7, v149, v243
	s_waitcnt vmcnt(3)
	v_fmac_f32_e32 v10, v150, v244
	v_fmac_f32_e32 v11, v151, v244
	v_fmac_f32_e32 v6, v152, v244
	v_fmac_f32_e32 v7, v153, v244
	s_waitcnt vmcnt(2)
	v_fmac_f32_e32 v10, v154, v245
	v_fmac_f32_e32 v11, v155, v245
	v_fmac_f32_e32 v6, v156, v245
	v_fmac_f32_e32 v7, v157, v245
	s_waitcnt vmcnt(1)
	v_fmac_f32_e32 v10, v158, v246
	v_fmac_f32_e32 v11, v159, v246
	v_fmac_f32_e32 v6, v160, v246
	v_fmac_f32_e32 v7, v161, v246
	s_waitcnt vmcnt(0)
	v_fmac_f32_e32 v10, v180, v247
	v_fmac_f32_e32 v11, v181, v247
	v_fmac_f32_e32 v6, v182, v247
	v_fmac_f32_e32 v7, v183, v247
	s_mov_b64 s[4:5], 0x4000
	s_or_b64 exec, exec, s[0:1]
